# GEMM main loops: first K iteration peeled with C=0 MFMAs, per-tile accumulator zero fill removed
# speedup vs baseline: 1.0112x; 1.0103x over previous
.LBB1_93:
	s_ashr_i32 s19, s18, 31
	s_lshl_b64 s[20:21], s[18:19], 19
	s_add_u32 s20, s33, s20
	s_addc_u32 s21, s34, s21
	s_and_b64 s[22:23], s[0:1], exec
	s_cselect_b32 s5, s21, s27
	s_cselect_b32 s19, s20, s26
	s_ashr_i32 s17, s16, 31
	s_lshl_b64 s[22:23], s[16:17], 19
	s_add_u32 s22, s35, s22
	s_addc_u32 s23, s36, s23
	s_and_b64 s[30:31], s[0:1], exec
	s_cselect_b32 s17, s23, s29
	s_cselect_b32 s25, s22, s28
	s_add_u32 s26, s26, 0x40080
	s_addc_u32 s27, s27, 0
	s_add_u32 s52, s28, 0x100
	s_addc_u32 s53, s29, 0
	s_mov_b32 s54, -2
	ds_read_b128 v[148:151], v153
	ds_read_b128 v[156:159], v153 offset:1024
	ds_read_b128 v[160:163], v153 offset:2048
	ds_read_b128 v[164:167], v153 offset:3072
	ds_read_b128 v[168:171], v154
	ds_read_b128 v[172:175], v154 offset:1024
	ds_read_b128 v[176:179], v154 offset:2048
	ds_read_b128 v[180:183], v154 offset:3072
	s_add_u32 s28, s26, 0xfffc0080
	s_addc_u32 s29, s27, -1
	s_cmp_eq_u32 s54, 12
	s_cselect_b32 s31, s5, s29
	s_cselect_b32 s30, s19, s28
	s_cselect_b32 s29, s17, s53
	s_cselect_b32 s28, s25, s52
	v_lshl_add_u64 v[216:217], s[26:27], 0, v[140:141]
	s_add_i32 m0, s38, 0xc000
	ds_read_b128 v[184:187], v155
	ds_read_b128 v[188:191], v155 offset:1024
	ds_read_b128 v[192:195], v155 offset:2048
	ds_read_b128 v[196:199], v155 offset:3072
	ds_read_b128 v[200:203], v155 offset:4096
	ds_read_b128 v[204:207], v155 offset:5120
	ds_read_b128 v[208:211], v155 offset:6144
	ds_read_b128 v[212:215], v155 offset:7168
	global_load_lds_dwordx4 v[216:217], off
	v_lshl_add_u64 v[216:217], s[26:27], 0, v[142:143]
	s_add_i32 m0, s38, 0xe000
	s_nop 0
	global_load_lds_dwordx4 v[216:217], off
	s_waitcnt vmcnt(8)
	s_waitcnt lgkmcnt(0)
	s_barrier
	s_setprio 1
	s_waitcnt lgkmcnt(0)
	v_mfma_f32_16x16x32_bf16 v[124:127], v[148:151], v[184:187], 0
	v_mfma_f32_16x16x32_bf16 v[120:123], v[160:163], v[184:187], 0
	v_mfma_f32_16x16x32_bf16 v[108:111], v[148:151], v[192:195], 0
	v_mfma_f32_16x16x32_bf16 v[104:107], v[160:163], v[192:195], 0
	v_mfma_f32_16x16x32_bf16 v[92:95], v[148:151], v[200:203], 0
	v_mfma_f32_16x16x32_bf16 v[88:91], v[160:163], v[200:203], 0
	v_mfma_f32_16x16x32_bf16 v[76:79], v[148:151], v[208:211], 0
	v_mfma_f32_16x16x32_bf16 v[72:75], v[160:163], v[208:211], 0
	v_mfma_f32_16x16x32_bf16 v[124:127], v[156:159], v[188:191], v[124:127]
	v_mfma_f32_16x16x32_bf16 v[120:123], v[164:167], v[188:191], v[120:123]
	v_mfma_f32_16x16x32_bf16 v[108:111], v[156:159], v[196:199], v[108:111]
	v_mfma_f32_16x16x32_bf16 v[104:107], v[164:167], v[196:199], v[104:107]
	v_mfma_f32_16x16x32_bf16 v[92:95], v[156:159], v[204:207], v[92:95]
	v_mfma_f32_16x16x32_bf16 v[88:91], v[164:167], v[204:207], v[88:91]
	v_mfma_f32_16x16x32_bf16 v[76:79], v[156:159], v[212:215], v[76:79]
	v_mfma_f32_16x16x32_bf16 v[72:75], v[164:167], v[212:215], v[72:75]
	s_setprio 0
	s_setprio 1
	v_mfma_f32_16x16x32_bf16 v[116:119], v[168:171], v[184:187], 0
	v_mfma_f32_16x16x32_bf16 v[112:115], v[176:179], v[184:187], 0
	v_mfma_f32_16x16x32_bf16 v[100:103], v[168:171], v[192:195], 0
	v_mfma_f32_16x16x32_bf16 v[96:99], v[176:179], v[192:195], 0
	v_mfma_f32_16x16x32_bf16 v[84:87], v[168:171], v[200:203], 0
	v_mfma_f32_16x16x32_bf16 v[80:83], v[176:179], v[200:203], 0
	v_mfma_f32_16x16x32_bf16 v[68:71], v[168:171], v[208:211], 0
	v_mfma_f32_16x16x32_bf16 v[64:67], v[176:179], v[208:211], 0
	v_mfma_f32_16x16x32_bf16 v[116:119], v[172:175], v[188:191], v[116:119]
	v_mfma_f32_16x16x32_bf16 v[112:115], v[180:183], v[188:191], v[112:115]
	v_mfma_f32_16x16x32_bf16 v[100:103], v[172:175], v[196:199], v[100:103]
	v_mfma_f32_16x16x32_bf16 v[96:99], v[180:183], v[196:199], v[96:99]
	v_mfma_f32_16x16x32_bf16 v[84:87], v[172:175], v[204:207], v[84:87]
	v_mfma_f32_16x16x32_bf16 v[80:83], v[180:183], v[204:207], v[80:83]
	v_mfma_f32_16x16x32_bf16 v[68:71], v[172:175], v[212:215], v[68:71]
	v_mfma_f32_16x16x32_bf16 v[64:67], v[180:183], v[212:215], v[64:67]
	s_setprio 0
	s_barrier
	s_add_i32 s55, s48, s37
	v_lshl_add_u64 v[216:217], s[28:29], 0, v[130:131]
	s_mov_b32 m0, s55
	ds_read_b128 v[184:187], v155 offset:16384
	ds_read_b128 v[188:191], v155 offset:17408
	ds_read_b128 v[192:195], v155 offset:18432
	ds_read_b128 v[196:199], v155 offset:19456
	ds_read_b128 v[200:203], v155 offset:20480
	ds_read_b128 v[204:207], v155 offset:21504
	ds_read_b128 v[208:211], v155 offset:22528
	ds_read_b128 v[212:215], v155 offset:23552
	global_load_lds_dwordx4 v[216:217], off
	s_add_i32 m0, s55, 0x2000
	s_add_u32 s56, s28, 0x40000
	v_lshl_add_u64 v[218:219], s[28:29], 0, v[134:135]
	s_addc_u32 s57, s29, 0
	s_add_i32 s55, s49, s37
	global_load_lds_dwordx4 v[218:219], off
	v_lshl_add_u64 v[220:221], s[56:57], 0, v[130:131]
	s_mov_b32 m0, s55
	v_lshl_add_u64 v[222:223], s[30:31], 0, v[132:133]
	global_load_lds_dwordx4 v[220:221], off
	v_lshl_add_u64 v[220:221], s[56:57], 0, v[134:135]
	s_add_i32 m0, s55, 0x2000
	s_nop 0
	global_load_lds_dwordx4 v[220:221], off
	v_lshl_add_u64 v[220:221], s[30:31], 0, v[128:129]
	s_mov_b32 m0, s38
	s_nop 0
	global_load_lds_dwordx4 v[220:221], off
	s_mov_b32 m0, s39
	s_nop 0
	global_load_lds_dwordx4 v[222:223], off
	s_waitcnt vmcnt(8)
	s_waitcnt lgkmcnt(0)
	s_barrier
	s_setprio 1
	s_waitcnt lgkmcnt(0)
	v_mfma_f32_16x16x32_bf16 v[60:63], v[148:151], v[184:187], 0
	v_mfma_f32_16x16x32_bf16 v[56:59], v[160:163], v[184:187], 0
	v_mfma_f32_16x16x32_bf16 v[44:47], v[148:151], v[192:195], 0
	v_mfma_f32_16x16x32_bf16 v[40:43], v[160:163], v[192:195], 0
	v_mfma_f32_16x16x32_bf16 v[28:31], v[148:151], v[200:203], 0
	v_mfma_f32_16x16x32_bf16 v[24:27], v[160:163], v[200:203], 0
	v_mfma_f32_16x16x32_bf16 v[12:15], v[148:151], v[208:211], 0
	v_mfma_f32_16x16x32_bf16 v[8:11], v[160:163], v[208:211], 0
	v_mfma_f32_16x16x32_bf16 v[60:63], v[156:159], v[188:191], v[60:63]
	v_mfma_f32_16x16x32_bf16 v[56:59], v[164:167], v[188:191], v[56:59]
	v_mfma_f32_16x16x32_bf16 v[44:47], v[156:159], v[196:199], v[44:47]
	v_mfma_f32_16x16x32_bf16 v[40:43], v[164:167], v[196:199], v[40:43]
	v_mfma_f32_16x16x32_bf16 v[28:31], v[156:159], v[204:207], v[28:31]
	v_mfma_f32_16x16x32_bf16 v[24:27], v[164:167], v[204:207], v[24:27]
	v_mfma_f32_16x16x32_bf16 v[12:15], v[156:159], v[212:215], v[12:15]
	v_mfma_f32_16x16x32_bf16 v[8:11], v[164:167], v[212:215], v[8:11]
	s_setprio 0
	s_setprio 1
	v_mfma_f32_16x16x32_bf16 v[52:55], v[168:171], v[184:187], 0
	v_mfma_f32_16x16x32_bf16 v[48:51], v[176:179], v[184:187], 0
	v_mfma_f32_16x16x32_bf16 v[36:39], v[168:171], v[192:195], 0
	v_mfma_f32_16x16x32_bf16 v[32:35], v[176:179], v[192:195], 0
	v_mfma_f32_16x16x32_bf16 v[20:23], v[168:171], v[200:203], 0
	v_mfma_f32_16x16x32_bf16 v[16:19], v[176:179], v[200:203], 0
	v_mfma_f32_16x16x32_bf16 v[4:7], v[168:171], v[208:211], 0
	v_mfma_f32_16x16x32_bf16 v[0:3], v[176:179], v[208:211], 0
	v_mfma_f32_16x16x32_bf16 v[52:55], v[172:175], v[188:191], v[52:55]
	v_mfma_f32_16x16x32_bf16 v[48:51], v[180:183], v[188:191], v[48:51]
	v_mfma_f32_16x16x32_bf16 v[36:39], v[172:175], v[196:199], v[36:39]
	v_mfma_f32_16x16x32_bf16 v[32:35], v[180:183], v[196:199], v[32:35]
	v_mfma_f32_16x16x32_bf16 v[20:23], v[172:175], v[204:207], v[20:23]
	v_mfma_f32_16x16x32_bf16 v[16:19], v[180:183], v[204:207], v[16:19]
	v_mfma_f32_16x16x32_bf16 v[4:7], v[172:175], v[212:215], v[4:7]
	v_mfma_f32_16x16x32_bf16 v[0:3], v[180:183], v[212:215], v[0:3]
	s_setprio 0
	s_barrier
	s_add_i32 s55, 0, 0x18000
	s_add_i32 s56, 0, 0x1c000
	v_add_u32_e32 v164, s55, v152
	v_add_u32_e32 v180, s56, v152
	ds_read_b128 v[148:151], v164
	ds_read_b128 v[156:159], v164 offset:1024
	ds_read_b128 v[160:163], v164 offset:2048
	ds_read_b128 v[164:167], v164 offset:3072
	ds_read_b128 v[168:171], v180
	ds_read_b128 v[172:175], v180 offset:1024
	ds_read_b128 v[176:179], v180 offset:2048
	ds_read_b128 v[180:183], v180 offset:3072
	s_add_u32 s30, s30, 0x40000
	s_addc_u32 s31, s31, 0
	s_mov_b32 m0, s40
	v_lshl_add_u64 v[224:225], s[30:31], 0, v[128:129]
	ds_read_b128 v[184:187], v155 offset:32768
	ds_read_b128 v[188:191], v155 offset:33792
	ds_read_b128 v[192:195], v155 offset:34816
	ds_read_b128 v[196:199], v155 offset:35840
	ds_read_b128 v[200:203], v155 offset:36864
	ds_read_b128 v[204:207], v155 offset:37888
	ds_read_b128 v[208:211], v155 offset:38912
	ds_read_b128 v[212:215], v155 offset:39936
	global_load_lds_dwordx4 v[224:225], off
	v_lshl_add_u64 v[224:225], s[30:31], 0, v[132:133]
	s_mov_b32 m0, s41
	s_nop 0
	global_load_lds_dwordx4 v[224:225], off
	s_waitcnt vmcnt(8)
	s_waitcnt lgkmcnt(0)
	s_barrier
	s_setprio 1
	s_waitcnt lgkmcnt(0)
	v_mfma_f32_16x16x32_bf16 v[124:127], v[148:151], v[184:187], v[124:127]
	v_mfma_f32_16x16x32_bf16 v[120:123], v[160:163], v[184:187], v[120:123]
	v_mfma_f32_16x16x32_bf16 v[108:111], v[148:151], v[192:195], v[108:111]
	v_mfma_f32_16x16x32_bf16 v[104:107], v[160:163], v[192:195], v[104:107]
	v_mfma_f32_16x16x32_bf16 v[92:95], v[148:151], v[200:203], v[92:95]
	v_mfma_f32_16x16x32_bf16 v[88:91], v[160:163], v[200:203], v[88:91]
	v_mfma_f32_16x16x32_bf16 v[76:79], v[148:151], v[208:211], v[76:79]
	v_mfma_f32_16x16x32_bf16 v[72:75], v[160:163], v[208:211], v[72:75]
	v_mfma_f32_16x16x32_bf16 v[124:127], v[156:159], v[188:191], v[124:127]
	v_mfma_f32_16x16x32_bf16 v[120:123], v[164:167], v[188:191], v[120:123]
	v_mfma_f32_16x16x32_bf16 v[108:111], v[156:159], v[196:199], v[108:111]
	v_mfma_f32_16x16x32_bf16 v[104:107], v[164:167], v[196:199], v[104:107]
	v_mfma_f32_16x16x32_bf16 v[92:95], v[156:159], v[204:207], v[92:95]
	v_mfma_f32_16x16x32_bf16 v[88:91], v[164:167], v[204:207], v[88:91]
	v_mfma_f32_16x16x32_bf16 v[76:79], v[156:159], v[212:215], v[76:79]
	v_mfma_f32_16x16x32_bf16 v[72:75], v[164:167], v[212:215], v[72:75]
	s_setprio 0
	s_setprio 1
	v_mfma_f32_16x16x32_bf16 v[116:119], v[168:171], v[184:187], v[116:119]
	v_mfma_f32_16x16x32_bf16 v[112:115], v[176:179], v[184:187], v[112:115]
	v_mfma_f32_16x16x32_bf16 v[100:103], v[168:171], v[192:195], v[100:103]
	v_mfma_f32_16x16x32_bf16 v[96:99], v[176:179], v[192:195], v[96:99]
	v_mfma_f32_16x16x32_bf16 v[84:87], v[168:171], v[200:203], v[84:87]
	v_mfma_f32_16x16x32_bf16 v[80:83], v[176:179], v[200:203], v[80:83]
	v_mfma_f32_16x16x32_bf16 v[68:71], v[168:171], v[208:211], v[68:71]
	v_mfma_f32_16x16x32_bf16 v[64:67], v[176:179], v[208:211], v[64:67]
	v_mfma_f32_16x16x32_bf16 v[116:119], v[172:175], v[188:191], v[116:119]
	v_mfma_f32_16x16x32_bf16 v[112:115], v[180:183], v[188:191], v[112:115]
	v_mfma_f32_16x16x32_bf16 v[100:103], v[172:175], v[196:199], v[100:103]
	v_mfma_f32_16x16x32_bf16 v[96:99], v[180:183], v[196:199], v[96:99]
	v_mfma_f32_16x16x32_bf16 v[84:87], v[172:175], v[204:207], v[84:87]
	v_mfma_f32_16x16x32_bf16 v[80:83], v[180:183], v[204:207], v[80:83]
	v_mfma_f32_16x16x32_bf16 v[68:71], v[172:175], v[212:215], v[68:71]
	v_mfma_f32_16x16x32_bf16 v[64:67], v[180:183], v[212:215], v[64:67]
	s_setprio 0
	s_barrier
	s_add_i32 s30, s55, s37
	v_lshl_add_u64 v[216:217], v[216:217], 0, s[12:13]
	s_mov_b32 m0, s30
	ds_read_b128 v[184:187], v155 offset:49152
	ds_read_b128 v[188:191], v155 offset:50176
	ds_read_b128 v[192:195], v155 offset:51200
	ds_read_b128 v[196:199], v155 offset:52224
	ds_read_b128 v[200:203], v155 offset:53248
	ds_read_b128 v[204:207], v155 offset:54272
	ds_read_b128 v[208:211], v155 offset:55296
	ds_read_b128 v[212:215], v155 offset:56320
	global_load_lds_dwordx4 v[216:217], off
	s_add_i32 m0, s30, 0x2000
	s_add_u32 s28, s28, 0x40080
	v_lshl_add_u64 v[216:217], v[218:219], 0, s[12:13]
	s_addc_u32 s29, s29, 0
	s_add_i32 s30, s56, s37
	global_load_lds_dwordx4 v[216:217], off
	v_lshl_add_u64 v[216:217], s[28:29], 0, v[130:131]
	s_mov_b32 m0, s30
	s_nop 0
	global_load_lds_dwordx4 v[216:217], off
	v_lshl_add_u64 v[216:217], s[28:29], 0, v[134:135]
	s_add_i32 m0, s30, 0x2000
	s_nop 0
	global_load_lds_dwordx4 v[216:217], off
	v_lshl_add_u64 v[216:217], v[220:221], 0, s[12:13]
	s_mov_b32 m0, s43
	s_nop 0
	global_load_lds_dwordx4 v[216:217], off
	v_lshl_add_u64 v[216:217], v[222:223], 0, s[12:13]
	s_mov_b32 m0, s44
	s_nop 0
	global_load_lds_dwordx4 v[216:217], off
	s_waitcnt vmcnt(8)
	s_waitcnt lgkmcnt(0)
	s_barrier
	s_setprio 1
	s_waitcnt lgkmcnt(0)
	v_mfma_f32_16x16x32_bf16 v[60:63], v[148:151], v[184:187], v[60:63]
	v_mfma_f32_16x16x32_bf16 v[56:59], v[160:163], v[184:187], v[56:59]
	v_mfma_f32_16x16x32_bf16 v[44:47], v[148:151], v[192:195], v[44:47]
	v_mfma_f32_16x16x32_bf16 v[40:43], v[160:163], v[192:195], v[40:43]
	v_mfma_f32_16x16x32_bf16 v[28:31], v[148:151], v[200:203], v[28:31]
	v_mfma_f32_16x16x32_bf16 v[24:27], v[160:163], v[200:203], v[24:27]
	v_mfma_f32_16x16x32_bf16 v[12:15], v[148:151], v[208:211], v[12:15]
	v_mfma_f32_16x16x32_bf16 v[8:11], v[160:163], v[208:211], v[8:11]
	v_mfma_f32_16x16x32_bf16 v[60:63], v[156:159], v[188:191], v[60:63]
	v_mfma_f32_16x16x32_bf16 v[56:59], v[164:167], v[188:191], v[56:59]
	v_mfma_f32_16x16x32_bf16 v[44:47], v[156:159], v[196:199], v[44:47]
	v_mfma_f32_16x16x32_bf16 v[40:43], v[164:167], v[196:199], v[40:43]
	v_mfma_f32_16x16x32_bf16 v[28:31], v[156:159], v[204:207], v[28:31]
	v_mfma_f32_16x16x32_bf16 v[24:27], v[164:167], v[204:207], v[24:27]
	v_mfma_f32_16x16x32_bf16 v[12:15], v[156:159], v[212:215], v[12:15]
	v_mfma_f32_16x16x32_bf16 v[8:11], v[164:167], v[212:215], v[8:11]
	s_setprio 0
	s_setprio 1
	v_mfma_f32_16x16x32_bf16 v[52:55], v[168:171], v[184:187], v[52:55]
	v_mfma_f32_16x16x32_bf16 v[48:51], v[176:179], v[184:187], v[48:51]
	v_mfma_f32_16x16x32_bf16 v[36:39], v[168:171], v[192:195], v[36:39]
	v_mfma_f32_16x16x32_bf16 v[32:35], v[176:179], v[192:195], v[32:35]
	v_mfma_f32_16x16x32_bf16 v[20:23], v[168:171], v[200:203], v[20:23]
	v_mfma_f32_16x16x32_bf16 v[16:19], v[176:179], v[200:203], v[16:19]
	v_mfma_f32_16x16x32_bf16 v[4:7], v[168:171], v[208:211], v[4:7]
	v_mfma_f32_16x16x32_bf16 v[0:3], v[176:179], v[208:211], v[0:3]
	v_mfma_f32_16x16x32_bf16 v[52:55], v[172:175], v[188:191], v[52:55]
	v_mfma_f32_16x16x32_bf16 v[48:51], v[180:183], v[188:191], v[48:51]
	v_mfma_f32_16x16x32_bf16 v[36:39], v[172:175], v[196:199], v[36:39]
	v_mfma_f32_16x16x32_bf16 v[32:35], v[180:183], v[196:199], v[32:35]
	v_mfma_f32_16x16x32_bf16 v[20:23], v[172:175], v[204:207], v[20:23]
	v_mfma_f32_16x16x32_bf16 v[16:19], v[180:183], v[204:207], v[16:19]
	v_mfma_f32_16x16x32_bf16 v[4:7], v[172:175], v[212:215], v[4:7]
	v_mfma_f32_16x16x32_bf16 v[0:3], v[180:183], v[212:215], v[0:3]
	s_setprio 0
	s_barrier
	s_add_i32 s54, s54, 2
	s_add_u32 s26, s26, 0x100
	s_addc_u32 s27, s27, 0
	s_add_u32 s52, s52, 0x100
	s_addc_u32 s53, s53, 0
	s_cmp_gt_u32 s54, 13

.LBB3_19:
	s_ashr_i32 s17, s16, 31
	s_lshl_b64 s[18:19], s[16:17], 19
	s_add_u32 s18, s33, s18
	v_cmp_lt_i64_e64 s[4:5], s[4:5], v[142:143]
	s_addc_u32 s19, s34, s19
	s_and_b64 s[20:21], s[4:5], exec
	s_cselect_b32 s17, s19, s25
	s_cselect_b32 s53, s18, s24
	s_ashr_i32 s15, s14, 31
	s_lshl_b64 s[20:21], s[14:15], 19
	s_add_u32 s20, s6, s20
	s_addc_u32 s21, s7, s21
	s_and_b64 s[28:29], s[4:5], exec
	s_cselect_b32 s15, s21, s27
	s_cselect_b32 s54, s20, s26
	s_add_u32 s24, s24, 0x40080
	s_addc_u32 s25, s25, 0
	s_add_u32 s55, s26, 0x100
	s_addc_u32 s56, s27, 0
	s_mov_b32 s57, -2
	ds_read_b128 v[152:155], v149
	ds_read_b128 v[156:159], v149 offset:1024
	ds_read_b128 v[160:163], v149 offset:2048
	ds_read_b128 v[164:167], v149 offset:3072
	ds_read_b128 v[168:171], v150
	ds_read_b128 v[172:175], v150 offset:1024
	ds_read_b128 v[176:179], v150 offset:2048
	ds_read_b128 v[180:183], v150 offset:3072
	s_add_u32 s26, s24, 0xfffc0080
	s_addc_u32 s27, s25, -1
	s_cmp_eq_u32 s57, 12
	s_cselect_b32 s29, s17, s27
	s_cselect_b32 s28, s53, s26
	s_cselect_b32 s27, s15, s56
	s_cselect_b32 s26, s54, s55
	v_lshl_add_u64 v[146:147], s[24:25], 0, v[138:139]
	s_add_i32 m0, s23, 0xc000
	ds_read_b128 v[184:187], v151
	ds_read_b128 v[188:191], v151 offset:1024
	ds_read_b128 v[192:195], v151 offset:2048
	ds_read_b128 v[196:199], v151 offset:3072
	ds_read_b128 v[200:203], v151 offset:4096
	ds_read_b128 v[204:207], v151 offset:5120
	ds_read_b128 v[208:211], v151 offset:6144
	ds_read_b128 v[212:215], v151 offset:7168
	global_load_lds_dwordx4 v[146:147], off
	v_lshl_add_u64 v[146:147], s[24:25], 0, v[140:141]
	s_add_i32 m0, s23, 0xe000
	s_nop 0
	global_load_lds_dwordx4 v[146:147], off
	s_waitcnt vmcnt(8)
	s_waitcnt lgkmcnt(0)
	s_barrier
	s_setprio 1
	s_waitcnt lgkmcnt(0)
	v_mfma_f32_16x16x32_bf16 v[124:127], v[152:155], v[184:187], 0
	v_mfma_f32_16x16x32_bf16 v[120:123], v[160:163], v[184:187], 0
	v_mfma_f32_16x16x32_bf16 v[116:119], v[152:155], v[192:195], 0
	v_mfma_f32_16x16x32_bf16 v[108:111], v[160:163], v[192:195], 0
	v_mfma_f32_16x16x32_bf16 v[100:103], v[152:155], v[200:203], 0
	v_mfma_f32_16x16x32_bf16 v[92:95], v[160:163], v[200:203], 0
	v_mfma_f32_16x16x32_bf16 v[84:87], v[152:155], v[208:211], 0
	v_mfma_f32_16x16x32_bf16 v[76:79], v[160:163], v[208:211], 0
	v_mfma_f32_16x16x32_bf16 v[124:127], v[156:159], v[188:191], v[124:127]
	v_mfma_f32_16x16x32_bf16 v[120:123], v[164:167], v[188:191], v[120:123]
	v_mfma_f32_16x16x32_bf16 v[116:119], v[156:159], v[196:199], v[116:119]
	v_mfma_f32_16x16x32_bf16 v[108:111], v[164:167], v[196:199], v[108:111]
	v_mfma_f32_16x16x32_bf16 v[100:103], v[156:159], v[204:207], v[100:103]
	v_mfma_f32_16x16x32_bf16 v[92:95], v[164:167], v[204:207], v[92:95]
	v_mfma_f32_16x16x32_bf16 v[84:87], v[156:159], v[212:215], v[84:87]
	v_mfma_f32_16x16x32_bf16 v[76:79], v[164:167], v[212:215], v[76:79]
	s_setprio 0
	s_setprio 1
	v_mfma_f32_16x16x32_bf16 v[112:115], v[168:171], v[184:187], 0
	v_mfma_f32_16x16x32_bf16 v[104:107], v[176:179], v[184:187], 0
	v_mfma_f32_16x16x32_bf16 v[96:99], v[168:171], v[192:195], 0
	v_mfma_f32_16x16x32_bf16 v[88:91], v[176:179], v[192:195], 0
	v_mfma_f32_16x16x32_bf16 v[80:83], v[168:171], v[200:203], 0
	v_mfma_f32_16x16x32_bf16 v[72:75], v[176:179], v[200:203], 0
	v_mfma_f32_16x16x32_bf16 v[68:71], v[168:171], v[208:211], 0
	v_mfma_f32_16x16x32_bf16 v[64:67], v[176:179], v[208:211], 0
	v_mfma_f32_16x16x32_bf16 v[112:115], v[172:175], v[188:191], v[112:115]
	v_mfma_f32_16x16x32_bf16 v[104:107], v[180:183], v[188:191], v[104:107]
	v_mfma_f32_16x16x32_bf16 v[96:99], v[172:175], v[196:199], v[96:99]
	v_mfma_f32_16x16x32_bf16 v[88:91], v[180:183], v[196:199], v[88:91]
	v_mfma_f32_16x16x32_bf16 v[80:83], v[172:175], v[204:207], v[80:83]
	v_mfma_f32_16x16x32_bf16 v[72:75], v[180:183], v[204:207], v[72:75]
	v_mfma_f32_16x16x32_bf16 v[68:71], v[172:175], v[212:215], v[68:71]
	v_mfma_f32_16x16x32_bf16 v[64:67], v[180:183], v[212:215], v[64:67]
	s_setprio 0
	s_barrier
	s_add_i32 s58, s45, s31
	v_lshl_add_u64 v[146:147], s[26:27], 0, v[130:131]
	s_mov_b32 m0, s58
	ds_read_b128 v[184:187], v151 offset:16384
	ds_read_b128 v[188:191], v151 offset:17408
	ds_read_b128 v[192:195], v151 offset:18432
	ds_read_b128 v[196:199], v151 offset:19456
	ds_read_b128 v[200:203], v151 offset:20480
	ds_read_b128 v[204:207], v151 offset:21504
	ds_read_b128 v[208:211], v151 offset:22528
	ds_read_b128 v[212:215], v151 offset:23552
	global_load_lds_dwordx4 v[146:147], off
	s_add_i32 m0, s58, 0x2000
	s_add_u32 s58, s26, 0x40000
	v_lshl_add_u64 v[216:217], s[26:27], 0, v[134:135]
	s_addc_u32 s59, s27, 0
	s_add_i32 s60, s46, s31
	global_load_lds_dwordx4 v[216:217], off
	v_lshl_add_u64 v[218:219], s[58:59], 0, v[130:131]
	s_mov_b32 m0, s60
	v_lshl_add_u64 v[220:221], s[28:29], 0, v[132:133]
	global_load_lds_dwordx4 v[218:219], off
	v_lshl_add_u64 v[218:219], s[58:59], 0, v[134:135]
	s_add_i32 m0, s60, 0x2000
	s_nop 0
	global_load_lds_dwordx4 v[218:219], off
	v_lshl_add_u64 v[218:219], s[28:29], 0, v[128:129]
	s_mov_b32 m0, s23
	s_nop 0
	global_load_lds_dwordx4 v[218:219], off
	s_mov_b32 m0, s35
	s_nop 0
	global_load_lds_dwordx4 v[220:221], off
	s_waitcnt vmcnt(8)
	s_waitcnt lgkmcnt(0)
	s_barrier
	s_setprio 1
	s_waitcnt lgkmcnt(0)
	v_mfma_f32_16x16x32_bf16 v[60:63], v[152:155], v[184:187], 0
	v_mfma_f32_16x16x32_bf16 v[56:59], v[160:163], v[184:187], 0
	v_mfma_f32_16x16x32_bf16 v[52:55], v[152:155], v[192:195], 0
	v_mfma_f32_16x16x32_bf16 v[44:47], v[160:163], v[192:195], 0
	v_mfma_f32_16x16x32_bf16 v[36:39], v[152:155], v[200:203], 0
	v_mfma_f32_16x16x32_bf16 v[28:31], v[160:163], v[200:203], 0
	v_mfma_f32_16x16x32_bf16 v[20:23], v[152:155], v[208:211], 0
	v_mfma_f32_16x16x32_bf16 v[12:15], v[160:163], v[208:211], 0
	v_mfma_f32_16x16x32_bf16 v[60:63], v[156:159], v[188:191], v[60:63]
	v_mfma_f32_16x16x32_bf16 v[56:59], v[164:167], v[188:191], v[56:59]
	v_mfma_f32_16x16x32_bf16 v[52:55], v[156:159], v[196:199], v[52:55]
	v_mfma_f32_16x16x32_bf16 v[44:47], v[164:167], v[196:199], v[44:47]
	v_mfma_f32_16x16x32_bf16 v[36:39], v[156:159], v[204:207], v[36:39]
	v_mfma_f32_16x16x32_bf16 v[28:31], v[164:167], v[204:207], v[28:31]
	v_mfma_f32_16x16x32_bf16 v[20:23], v[156:159], v[212:215], v[20:23]
	v_mfma_f32_16x16x32_bf16 v[12:15], v[164:167], v[212:215], v[12:15]
	s_setprio 0
	s_setprio 1
	v_mfma_f32_16x16x32_bf16 v[48:51], v[168:171], v[184:187], 0
	v_mfma_f32_16x16x32_bf16 v[40:43], v[176:179], v[184:187], 0
	v_mfma_f32_16x16x32_bf16 v[32:35], v[168:171], v[192:195], 0
	v_mfma_f32_16x16x32_bf16 v[24:27], v[176:179], v[192:195], 0
	v_mfma_f32_16x16x32_bf16 v[16:19], v[168:171], v[200:203], 0
	v_mfma_f32_16x16x32_bf16 v[8:11], v[176:179], v[200:203], 0
	v_mfma_f32_16x16x32_bf16 v[4:7], v[168:171], v[208:211], 0
	v_mfma_f32_16x16x32_bf16 v[0:3], v[176:179], v[208:211], 0
	v_mfma_f32_16x16x32_bf16 v[48:51], v[172:175], v[188:191], v[48:51]
	v_mfma_f32_16x16x32_bf16 v[40:43], v[180:183], v[188:191], v[40:43]
	v_mfma_f32_16x16x32_bf16 v[32:35], v[172:175], v[196:199], v[32:35]
	v_mfma_f32_16x16x32_bf16 v[24:27], v[180:183], v[196:199], v[24:27]
	v_mfma_f32_16x16x32_bf16 v[16:19], v[172:175], v[204:207], v[16:19]
	v_mfma_f32_16x16x32_bf16 v[8:11], v[180:183], v[204:207], v[8:11]
	v_mfma_f32_16x16x32_bf16 v[4:7], v[172:175], v[212:215], v[4:7]
	v_mfma_f32_16x16x32_bf16 v[0:3], v[180:183], v[212:215], v[0:3]
	s_setprio 0
	s_barrier
	s_add_i32 s58, 0, 0x18000
	s_add_i32 s59, 0, 0x1c000
	v_add_u32_e32 v164, s58, v148
	v_add_u32_e32 v180, s59, v148
	ds_read_b128 v[152:155], v164
	ds_read_b128 v[156:159], v164 offset:1024
	ds_read_b128 v[160:163], v164 offset:2048
	ds_read_b128 v[164:167], v164 offset:3072
	ds_read_b128 v[168:171], v180
	ds_read_b128 v[172:175], v180 offset:1024
	ds_read_b128 v[176:179], v180 offset:2048
	ds_read_b128 v[180:183], v180 offset:3072
	s_add_u32 s28, s28, 0x40000
	s_addc_u32 s29, s29, 0
	s_mov_b32 m0, s36
	v_lshl_add_u64 v[222:223], s[28:29], 0, v[128:129]
	ds_read_b128 v[184:187], v151 offset:32768
	ds_read_b128 v[188:191], v151 offset:33792
	ds_read_b128 v[192:195], v151 offset:34816
	ds_read_b128 v[196:199], v151 offset:35840
	ds_read_b128 v[200:203], v151 offset:36864
	ds_read_b128 v[204:207], v151 offset:37888
	ds_read_b128 v[208:211], v151 offset:38912
	ds_read_b128 v[212:215], v151 offset:39936
	global_load_lds_dwordx4 v[222:223], off
	v_lshl_add_u64 v[222:223], s[28:29], 0, v[132:133]
	s_mov_b32 m0, s37
	s_nop 0
	global_load_lds_dwordx4 v[222:223], off
	s_waitcnt vmcnt(8)
	s_waitcnt lgkmcnt(0)
	s_barrier
	s_setprio 1
	s_waitcnt lgkmcnt(0)
	v_mfma_f32_16x16x32_bf16 v[124:127], v[152:155], v[184:187], v[124:127]
	v_mfma_f32_16x16x32_bf16 v[120:123], v[160:163], v[184:187], v[120:123]
	v_mfma_f32_16x16x32_bf16 v[116:119], v[152:155], v[192:195], v[116:119]
	v_mfma_f32_16x16x32_bf16 v[108:111], v[160:163], v[192:195], v[108:111]
	v_mfma_f32_16x16x32_bf16 v[100:103], v[152:155], v[200:203], v[100:103]
	v_mfma_f32_16x16x32_bf16 v[92:95], v[160:163], v[200:203], v[92:95]
	v_mfma_f32_16x16x32_bf16 v[84:87], v[152:155], v[208:211], v[84:87]
	v_mfma_f32_16x16x32_bf16 v[76:79], v[160:163], v[208:211], v[76:79]
	v_mfma_f32_16x16x32_bf16 v[124:127], v[156:159], v[188:191], v[124:127]
	v_mfma_f32_16x16x32_bf16 v[120:123], v[164:167], v[188:191], v[120:123]
	v_mfma_f32_16x16x32_bf16 v[116:119], v[156:159], v[196:199], v[116:119]
	v_mfma_f32_16x16x32_bf16 v[108:111], v[164:167], v[196:199], v[108:111]
	v_mfma_f32_16x16x32_bf16 v[100:103], v[156:159], v[204:207], v[100:103]
	v_mfma_f32_16x16x32_bf16 v[92:95], v[164:167], v[204:207], v[92:95]
	v_mfma_f32_16x16x32_bf16 v[84:87], v[156:159], v[212:215], v[84:87]
	v_mfma_f32_16x16x32_bf16 v[76:79], v[164:167], v[212:215], v[76:79]
	s_setprio 0
	s_setprio 1
	v_mfma_f32_16x16x32_bf16 v[112:115], v[168:171], v[184:187], v[112:115]
	v_mfma_f32_16x16x32_bf16 v[104:107], v[176:179], v[184:187], v[104:107]
	v_mfma_f32_16x16x32_bf16 v[96:99], v[168:171], v[192:195], v[96:99]
	v_mfma_f32_16x16x32_bf16 v[88:91], v[176:179], v[192:195], v[88:91]
	v_mfma_f32_16x16x32_bf16 v[80:83], v[168:171], v[200:203], v[80:83]
	v_mfma_f32_16x16x32_bf16 v[72:75], v[176:179], v[200:203], v[72:75]
	v_mfma_f32_16x16x32_bf16 v[68:71], v[168:171], v[208:211], v[68:71]
	v_mfma_f32_16x16x32_bf16 v[64:67], v[176:179], v[208:211], v[64:67]
	v_mfma_f32_16x16x32_bf16 v[112:115], v[172:175], v[188:191], v[112:115]
	v_mfma_f32_16x16x32_bf16 v[104:107], v[180:183], v[188:191], v[104:107]
	v_mfma_f32_16x16x32_bf16 v[96:99], v[172:175], v[196:199], v[96:99]
	v_mfma_f32_16x16x32_bf16 v[88:91], v[180:183], v[196:199], v[88:91]
	v_mfma_f32_16x16x32_bf16 v[80:83], v[172:175], v[204:207], v[80:83]
	v_mfma_f32_16x16x32_bf16 v[72:75], v[180:183], v[204:207], v[72:75]
	v_mfma_f32_16x16x32_bf16 v[68:71], v[172:175], v[212:215], v[68:71]
	v_mfma_f32_16x16x32_bf16 v[64:67], v[180:183], v[212:215], v[64:67]
	s_setprio 0
	s_barrier
	s_add_i32 s28, s58, s31
	v_lshl_add_u64 v[146:147], v[146:147], 0, s[12:13]
	s_mov_b32 m0, s28
	ds_read_b128 v[184:187], v151 offset:49152
	ds_read_b128 v[188:191], v151 offset:50176
	ds_read_b128 v[192:195], v151 offset:51200
	ds_read_b128 v[196:199], v151 offset:52224
	ds_read_b128 v[200:203], v151 offset:53248
	ds_read_b128 v[204:207], v151 offset:54272
	ds_read_b128 v[208:211], v151 offset:55296
	ds_read_b128 v[212:215], v151 offset:56320
	global_load_lds_dwordx4 v[146:147], off
	s_add_i32 m0, s28, 0x2000
	s_add_u32 s26, s26, 0x40080
	v_lshl_add_u64 v[146:147], v[216:217], 0, s[12:13]
	s_addc_u32 s27, s27, 0
	s_add_i32 s28, s59, s31
	global_load_lds_dwordx4 v[146:147], off
	v_lshl_add_u64 v[146:147], s[26:27], 0, v[130:131]
	s_mov_b32 m0, s28
	s_nop 0
	global_load_lds_dwordx4 v[146:147], off
	v_lshl_add_u64 v[146:147], s[26:27], 0, v[134:135]
	s_add_i32 m0, s28, 0x2000
	s_nop 0
	global_load_lds_dwordx4 v[146:147], off
	v_lshl_add_u64 v[146:147], v[218:219], 0, s[12:13]
	s_mov_b32 m0, s40
	s_nop 0
	global_load_lds_dwordx4 v[146:147], off
	v_lshl_add_u64 v[146:147], v[220:221], 0, s[12:13]
	s_mov_b32 m0, s41
	s_nop 0
	global_load_lds_dwordx4 v[146:147], off
	s_waitcnt vmcnt(8)
	s_waitcnt lgkmcnt(0)
	s_barrier
	s_setprio 1
	s_waitcnt lgkmcnt(0)
	v_mfma_f32_16x16x32_bf16 v[60:63], v[152:155], v[184:187], v[60:63]
	v_mfma_f32_16x16x32_bf16 v[56:59], v[160:163], v[184:187], v[56:59]
	v_mfma_f32_16x16x32_bf16 v[52:55], v[152:155], v[192:195], v[52:55]
	v_mfma_f32_16x16x32_bf16 v[44:47], v[160:163], v[192:195], v[44:47]
	v_mfma_f32_16x16x32_bf16 v[36:39], v[152:155], v[200:203], v[36:39]
	v_mfma_f32_16x16x32_bf16 v[28:31], v[160:163], v[200:203], v[28:31]
	v_mfma_f32_16x16x32_bf16 v[20:23], v[152:155], v[208:211], v[20:23]
	v_mfma_f32_16x16x32_bf16 v[12:15], v[160:163], v[208:211], v[12:15]
	v_mfma_f32_16x16x32_bf16 v[60:63], v[156:159], v[188:191], v[60:63]
	v_mfma_f32_16x16x32_bf16 v[56:59], v[164:167], v[188:191], v[56:59]
	v_mfma_f32_16x16x32_bf16 v[52:55], v[156:159], v[196:199], v[52:55]
	v_mfma_f32_16x16x32_bf16 v[44:47], v[164:167], v[196:199], v[44:47]
	v_mfma_f32_16x16x32_bf16 v[36:39], v[156:159], v[204:207], v[36:39]
	v_mfma_f32_16x16x32_bf16 v[28:31], v[164:167], v[204:207], v[28:31]
	v_mfma_f32_16x16x32_bf16 v[20:23], v[156:159], v[212:215], v[20:23]
	v_mfma_f32_16x16x32_bf16 v[12:15], v[164:167], v[212:215], v[12:15]
	s_setprio 0
	s_setprio 1
	v_mfma_f32_16x16x32_bf16 v[48:51], v[168:171], v[184:187], v[48:51]
	v_mfma_f32_16x16x32_bf16 v[40:43], v[176:179], v[184:187], v[40:43]
	v_mfma_f32_16x16x32_bf16 v[32:35], v[168:171], v[192:195], v[32:35]
	v_mfma_f32_16x16x32_bf16 v[24:27], v[176:179], v[192:195], v[24:27]
	v_mfma_f32_16x16x32_bf16 v[16:19], v[168:171], v[200:203], v[16:19]
	v_mfma_f32_16x16x32_bf16 v[8:11], v[176:179], v[200:203], v[8:11]
	v_mfma_f32_16x16x32_bf16 v[4:7], v[168:171], v[208:211], v[4:7]
	v_mfma_f32_16x16x32_bf16 v[0:3], v[176:179], v[208:211], v[0:3]
	v_mfma_f32_16x16x32_bf16 v[48:51], v[172:175], v[188:191], v[48:51]
	v_mfma_f32_16x16x32_bf16 v[40:43], v[180:183], v[188:191], v[40:43]
	v_mfma_f32_16x16x32_bf16 v[32:35], v[172:175], v[196:199], v[32:35]
	v_mfma_f32_16x16x32_bf16 v[24:27], v[180:183], v[196:199], v[24:27]
	v_mfma_f32_16x16x32_bf16 v[16:19], v[172:175], v[204:207], v[16:19]
	v_mfma_f32_16x16x32_bf16 v[8:11], v[180:183], v[204:207], v[8:11]
	v_mfma_f32_16x16x32_bf16 v[4:7], v[172:175], v[212:215], v[4:7]
	v_mfma_f32_16x16x32_bf16 v[0:3], v[180:183], v[212:215], v[0:3]
	s_setprio 0
	s_barrier
	s_add_i32 s57, s57, 2
	s_add_u32 s24, s24, 0x100
	s_addc_u32 s25, s25, 0
	s_add_u32 s55, s55, 0x100
	s_addc_u32 s56, s56, 0
	s_cmp_gt_u32 s57, 13

.LBB5_8:
	s_ashr_i32 s15, s14, 31
	s_lshl_b64 s[16:17], s[14:15], 19
	s_add_u32 s16, s28, s16
	v_cmp_lt_i64_e64 s[4:5], s[4:5], v[142:143]
	s_addc_u32 s17, s29, s17
	s_and_b64 s[18:19], s[4:5], exec
	s_cselect_b32 s15, s17, s23
	s_cselect_b32 s54, s16, s22
	s_ashr_i32 s13, s12, 31
	s_lshl_b64 s[18:19], s[12:13], 19
	s_add_u32 s18, s30, s18
	s_addc_u32 s19, s31, s19
	s_and_b64 s[26:27], s[4:5], exec
	s_cselect_b32 s13, s19, s25
	s_cselect_b32 s55, s18, s24
	s_add_u32 s22, s22, 0x40080
	s_addc_u32 s23, s23, 0
	s_add_u32 s56, s24, 0x100
	s_addc_u32 s57, s25, 0
	s_mov_b32 s58, -2
	ds_read_b128 v[152:155], v149
	ds_read_b128 v[156:159], v149 offset:1024
	ds_read_b128 v[160:163], v149 offset:2048
	ds_read_b128 v[164:167], v149 offset:3072
	ds_read_b128 v[168:171], v150
	ds_read_b128 v[172:175], v150 offset:1024
	ds_read_b128 v[176:179], v150 offset:2048
	ds_read_b128 v[180:183], v150 offset:3072
	s_add_u32 s24, s22, 0xfffc0080
	s_addc_u32 s25, s23, -1
	s_cmp_eq_u32 s58, 12
	s_cselect_b32 s27, s15, s25
	s_cselect_b32 s26, s54, s24
	s_cselect_b32 s25, s13, s57
	s_cselect_b32 s24, s55, s56
	v_lshl_add_u64 v[146:147], s[22:23], 0, v[138:139]
	s_add_i32 m0, s21, 0xc000
	ds_read_b128 v[184:187], v151
	ds_read_b128 v[188:191], v151 offset:1024
	ds_read_b128 v[192:195], v151 offset:2048
	ds_read_b128 v[196:199], v151 offset:3072
	ds_read_b128 v[200:203], v151 offset:4096
	ds_read_b128 v[204:207], v151 offset:5120
	ds_read_b128 v[208:211], v151 offset:6144
	ds_read_b128 v[212:215], v151 offset:7168
	global_load_lds_dwordx4 v[146:147], off
	v_lshl_add_u64 v[146:147], s[22:23], 0, v[140:141]
	s_add_i32 m0, s21, 0xe000
	s_nop 0
	global_load_lds_dwordx4 v[146:147], off
	s_waitcnt vmcnt(8)
	s_waitcnt lgkmcnt(0)
	s_barrier
	s_setprio 1
	s_waitcnt lgkmcnt(0)
	v_mfma_f32_16x16x32_bf16 v[124:127], v[152:155], v[184:187], 0
	v_mfma_f32_16x16x32_bf16 v[120:123], v[160:163], v[184:187], 0
	v_mfma_f32_16x16x32_bf16 v[108:111], v[152:155], v[192:195], 0
	v_mfma_f32_16x16x32_bf16 v[104:107], v[160:163], v[192:195], 0
	v_mfma_f32_16x16x32_bf16 v[92:95], v[152:155], v[200:203], 0
	v_mfma_f32_16x16x32_bf16 v[88:91], v[160:163], v[200:203], 0
	v_mfma_f32_16x16x32_bf16 v[76:79], v[152:155], v[208:211], 0
	v_mfma_f32_16x16x32_bf16 v[72:75], v[160:163], v[208:211], 0
	v_mfma_f32_16x16x32_bf16 v[124:127], v[156:159], v[188:191], v[124:127]
	v_mfma_f32_16x16x32_bf16 v[120:123], v[164:167], v[188:191], v[120:123]
	v_mfma_f32_16x16x32_bf16 v[108:111], v[156:159], v[196:199], v[108:111]
	v_mfma_f32_16x16x32_bf16 v[104:107], v[164:167], v[196:199], v[104:107]
	v_mfma_f32_16x16x32_bf16 v[92:95], v[156:159], v[204:207], v[92:95]
	v_mfma_f32_16x16x32_bf16 v[88:91], v[164:167], v[204:207], v[88:91]
	v_mfma_f32_16x16x32_bf16 v[76:79], v[156:159], v[212:215], v[76:79]
	v_mfma_f32_16x16x32_bf16 v[72:75], v[164:167], v[212:215], v[72:75]
	s_setprio 0
	s_setprio 1
	v_mfma_f32_16x16x32_bf16 v[116:119], v[168:171], v[184:187], 0
	v_mfma_f32_16x16x32_bf16 v[112:115], v[176:179], v[184:187], 0
	v_mfma_f32_16x16x32_bf16 v[100:103], v[168:171], v[192:195], 0
	v_mfma_f32_16x16x32_bf16 v[96:99], v[176:179], v[192:195], 0
	v_mfma_f32_16x16x32_bf16 v[84:87], v[168:171], v[200:203], 0
	v_mfma_f32_16x16x32_bf16 v[80:83], v[176:179], v[200:203], 0
	v_mfma_f32_16x16x32_bf16 v[68:71], v[168:171], v[208:211], 0
	v_mfma_f32_16x16x32_bf16 v[64:67], v[176:179], v[208:211], 0
	v_mfma_f32_16x16x32_bf16 v[116:119], v[172:175], v[188:191], v[116:119]
	v_mfma_f32_16x16x32_bf16 v[112:115], v[180:183], v[188:191], v[112:115]
	v_mfma_f32_16x16x32_bf16 v[100:103], v[172:175], v[196:199], v[100:103]
	v_mfma_f32_16x16x32_bf16 v[96:99], v[180:183], v[196:199], v[96:99]
	v_mfma_f32_16x16x32_bf16 v[84:87], v[172:175], v[204:207], v[84:87]
	v_mfma_f32_16x16x32_bf16 v[80:83], v[180:183], v[204:207], v[80:83]
	v_mfma_f32_16x16x32_bf16 v[68:71], v[172:175], v[212:215], v[68:71]
	v_mfma_f32_16x16x32_bf16 v[64:67], v[180:183], v[212:215], v[64:67]
	s_setprio 0
	s_barrier
	s_add_i32 s59, s43, s33
	v_lshl_add_u64 v[146:147], s[24:25], 0, v[132:133]
	s_mov_b32 m0, s59
	ds_read_b128 v[184:187], v151 offset:16384
	ds_read_b128 v[188:191], v151 offset:17408
	ds_read_b128 v[192:195], v151 offset:18432
	ds_read_b128 v[196:199], v151 offset:19456
	ds_read_b128 v[200:203], v151 offset:20480
	ds_read_b128 v[204:207], v151 offset:21504
	ds_read_b128 v[208:211], v151 offset:22528
	ds_read_b128 v[212:215], v151 offset:23552
	global_load_lds_dwordx4 v[146:147], off
	s_add_i32 m0, s59, 0x2000
	s_add_u32 s60, s24, 0x40000
	v_lshl_add_u64 v[216:217], s[24:25], 0, v[128:129]
	s_addc_u32 s61, s25, 0
	s_add_i32 s59, s44, s33
	global_load_lds_dwordx4 v[216:217], off
	v_lshl_add_u64 v[218:219], s[60:61], 0, v[132:133]
	s_mov_b32 m0, s59
	v_lshl_add_u64 v[220:221], s[26:27], 0, v[130:131]
	global_load_lds_dwordx4 v[218:219], off
	v_lshl_add_u64 v[218:219], s[60:61], 0, v[128:129]
	s_add_i32 m0, s59, 0x2000
	s_nop 0
	global_load_lds_dwordx4 v[218:219], off
	v_lshl_add_u64 v[218:219], s[26:27], 0, v[134:135]
	s_mov_b32 m0, s21
	s_nop 0
	global_load_lds_dwordx4 v[218:219], off
	s_mov_b32 m0, s36
	s_nop 0
	global_load_lds_dwordx4 v[220:221], off
	s_waitcnt vmcnt(8)
	s_waitcnt lgkmcnt(0)
	s_barrier
	s_setprio 1
	s_waitcnt lgkmcnt(0)
	v_mfma_f32_16x16x32_bf16 v[60:63], v[152:155], v[184:187], 0
	v_mfma_f32_16x16x32_bf16 v[56:59], v[160:163], v[184:187], 0
	v_mfma_f32_16x16x32_bf16 v[44:47], v[152:155], v[192:195], 0
	v_mfma_f32_16x16x32_bf16 v[40:43], v[160:163], v[192:195], 0
	v_mfma_f32_16x16x32_bf16 v[28:31], v[152:155], v[200:203], 0
	v_mfma_f32_16x16x32_bf16 v[24:27], v[160:163], v[200:203], 0
	v_mfma_f32_16x16x32_bf16 v[12:15], v[152:155], v[208:211], 0
	v_mfma_f32_16x16x32_bf16 v[8:11], v[160:163], v[208:211], 0
	v_mfma_f32_16x16x32_bf16 v[60:63], v[156:159], v[188:191], v[60:63]
	v_mfma_f32_16x16x32_bf16 v[56:59], v[164:167], v[188:191], v[56:59]
	v_mfma_f32_16x16x32_bf16 v[44:47], v[156:159], v[196:199], v[44:47]
	v_mfma_f32_16x16x32_bf16 v[40:43], v[164:167], v[196:199], v[40:43]
	v_mfma_f32_16x16x32_bf16 v[28:31], v[156:159], v[204:207], v[28:31]
	v_mfma_f32_16x16x32_bf16 v[24:27], v[164:167], v[204:207], v[24:27]
	v_mfma_f32_16x16x32_bf16 v[12:15], v[156:159], v[212:215], v[12:15]
	v_mfma_f32_16x16x32_bf16 v[8:11], v[164:167], v[212:215], v[8:11]
	s_setprio 0
	s_setprio 1
	v_mfma_f32_16x16x32_bf16 v[52:55], v[168:171], v[184:187], 0
	v_mfma_f32_16x16x32_bf16 v[48:51], v[176:179], v[184:187], 0
	v_mfma_f32_16x16x32_bf16 v[36:39], v[168:171], v[192:195], 0
	v_mfma_f32_16x16x32_bf16 v[32:35], v[176:179], v[192:195], 0
	v_mfma_f32_16x16x32_bf16 v[20:23], v[168:171], v[200:203], 0
	v_mfma_f32_16x16x32_bf16 v[16:19], v[176:179], v[200:203], 0
	v_mfma_f32_16x16x32_bf16 v[4:7], v[168:171], v[208:211], 0
	v_mfma_f32_16x16x32_bf16 v[0:3], v[176:179], v[208:211], 0
	v_mfma_f32_16x16x32_bf16 v[52:55], v[172:175], v[188:191], v[52:55]
	v_mfma_f32_16x16x32_bf16 v[48:51], v[180:183], v[188:191], v[48:51]
	v_mfma_f32_16x16x32_bf16 v[36:39], v[172:175], v[196:199], v[36:39]
	v_mfma_f32_16x16x32_bf16 v[32:35], v[180:183], v[196:199], v[32:35]
	v_mfma_f32_16x16x32_bf16 v[20:23], v[172:175], v[204:207], v[20:23]
	v_mfma_f32_16x16x32_bf16 v[16:19], v[180:183], v[204:207], v[16:19]
	v_mfma_f32_16x16x32_bf16 v[4:7], v[172:175], v[212:215], v[4:7]
	v_mfma_f32_16x16x32_bf16 v[0:3], v[180:183], v[212:215], v[0:3]
	s_setprio 0
	s_barrier
	s_add_i32 s59, 0, 0x18000
	s_add_i32 s60, 0, 0x1c000
	v_add_u32_e32 v164, s59, v148
	v_add_u32_e32 v180, s60, v148
	ds_read_b128 v[152:155], v164
	ds_read_b128 v[156:159], v164 offset:1024
	ds_read_b128 v[160:163], v164 offset:2048
	ds_read_b128 v[164:167], v164 offset:3072
	ds_read_b128 v[168:171], v180
	ds_read_b128 v[172:175], v180 offset:1024
	ds_read_b128 v[176:179], v180 offset:2048
	ds_read_b128 v[180:183], v180 offset:3072
	s_add_u32 s26, s26, 0x40000
	s_addc_u32 s27, s27, 0
	s_mov_b32 m0, s37
	v_lshl_add_u64 v[222:223], s[26:27], 0, v[134:135]
	ds_read_b128 v[184:187], v151 offset:32768
	ds_read_b128 v[188:191], v151 offset:33792
	ds_read_b128 v[192:195], v151 offset:34816
	ds_read_b128 v[196:199], v151 offset:35840
	ds_read_b128 v[200:203], v151 offset:36864
	ds_read_b128 v[204:207], v151 offset:37888
	ds_read_b128 v[208:211], v151 offset:38912
	ds_read_b128 v[212:215], v151 offset:39936
	global_load_lds_dwordx4 v[222:223], off
	v_lshl_add_u64 v[222:223], s[26:27], 0, v[130:131]
	s_mov_b32 m0, s38
	s_nop 0
	global_load_lds_dwordx4 v[222:223], off
	s_waitcnt vmcnt(8)
	s_waitcnt lgkmcnt(0)
	s_barrier
	s_setprio 1
	s_waitcnt lgkmcnt(0)
	v_mfma_f32_16x16x32_bf16 v[124:127], v[152:155], v[184:187], v[124:127]
	v_mfma_f32_16x16x32_bf16 v[120:123], v[160:163], v[184:187], v[120:123]
	v_mfma_f32_16x16x32_bf16 v[108:111], v[152:155], v[192:195], v[108:111]
	v_mfma_f32_16x16x32_bf16 v[104:107], v[160:163], v[192:195], v[104:107]
	v_mfma_f32_16x16x32_bf16 v[92:95], v[152:155], v[200:203], v[92:95]
	v_mfma_f32_16x16x32_bf16 v[88:91], v[160:163], v[200:203], v[88:91]
	v_mfma_f32_16x16x32_bf16 v[76:79], v[152:155], v[208:211], v[76:79]
	v_mfma_f32_16x16x32_bf16 v[72:75], v[160:163], v[208:211], v[72:75]
	v_mfma_f32_16x16x32_bf16 v[124:127], v[156:159], v[188:191], v[124:127]
	v_mfma_f32_16x16x32_bf16 v[120:123], v[164:167], v[188:191], v[120:123]
	v_mfma_f32_16x16x32_bf16 v[108:111], v[156:159], v[196:199], v[108:111]
	v_mfma_f32_16x16x32_bf16 v[104:107], v[164:167], v[196:199], v[104:107]
	v_mfma_f32_16x16x32_bf16 v[92:95], v[156:159], v[204:207], v[92:95]
	v_mfma_f32_16x16x32_bf16 v[88:91], v[164:167], v[204:207], v[88:91]
	v_mfma_f32_16x16x32_bf16 v[76:79], v[156:159], v[212:215], v[76:79]
	v_mfma_f32_16x16x32_bf16 v[72:75], v[164:167], v[212:215], v[72:75]
	s_setprio 0
	s_setprio 1
	v_mfma_f32_16x16x32_bf16 v[116:119], v[168:171], v[184:187], v[116:119]
	v_mfma_f32_16x16x32_bf16 v[112:115], v[176:179], v[184:187], v[112:115]
	v_mfma_f32_16x16x32_bf16 v[100:103], v[168:171], v[192:195], v[100:103]
	v_mfma_f32_16x16x32_bf16 v[96:99], v[176:179], v[192:195], v[96:99]
	v_mfma_f32_16x16x32_bf16 v[84:87], v[168:171], v[200:203], v[84:87]
	v_mfma_f32_16x16x32_bf16 v[80:83], v[176:179], v[200:203], v[80:83]
	v_mfma_f32_16x16x32_bf16 v[68:71], v[168:171], v[208:211], v[68:71]
	v_mfma_f32_16x16x32_bf16 v[64:67], v[176:179], v[208:211], v[64:67]
	v_mfma_f32_16x16x32_bf16 v[116:119], v[172:175], v[188:191], v[116:119]
	v_mfma_f32_16x16x32_bf16 v[112:115], v[180:183], v[188:191], v[112:115]
	v_mfma_f32_16x16x32_bf16 v[100:103], v[172:175], v[196:199], v[100:103]
	v_mfma_f32_16x16x32_bf16 v[96:99], v[180:183], v[196:199], v[96:99]
	v_mfma_f32_16x16x32_bf16 v[84:87], v[172:175], v[204:207], v[84:87]
	v_mfma_f32_16x16x32_bf16 v[80:83], v[180:183], v[204:207], v[80:83]
	v_mfma_f32_16x16x32_bf16 v[68:71], v[172:175], v[212:215], v[68:71]
	v_mfma_f32_16x16x32_bf16 v[64:67], v[180:183], v[212:215], v[64:67]
	s_setprio 0
	s_barrier
	s_add_i32 s26, s59, s33
	v_lshl_add_u64 v[146:147], v[146:147], 0, s[10:11]
	s_mov_b32 m0, s26
	ds_read_b128 v[184:187], v151 offset:49152
	ds_read_b128 v[188:191], v151 offset:50176
	ds_read_b128 v[192:195], v151 offset:51200
	ds_read_b128 v[196:199], v151 offset:52224
	ds_read_b128 v[200:203], v151 offset:53248
	ds_read_b128 v[204:207], v151 offset:54272
	ds_read_b128 v[208:211], v151 offset:55296
	ds_read_b128 v[212:215], v151 offset:56320
	global_load_lds_dwordx4 v[146:147], off
	s_add_i32 m0, s26, 0x2000
	s_add_u32 s24, s24, 0x40080
	v_lshl_add_u64 v[146:147], v[216:217], 0, s[10:11]
	s_addc_u32 s25, s25, 0
	s_add_i32 s26, s60, s33
	global_load_lds_dwordx4 v[146:147], off
	v_lshl_add_u64 v[146:147], s[24:25], 0, v[132:133]
	s_mov_b32 m0, s26
	s_nop 0
	global_load_lds_dwordx4 v[146:147], off
	v_lshl_add_u64 v[146:147], s[24:25], 0, v[128:129]
	s_add_i32 m0, s26, 0x2000
	s_nop 0
	global_load_lds_dwordx4 v[146:147], off
	v_lshl_add_u64 v[146:147], v[218:219], 0, s[10:11]
	s_mov_b32 m0, s40
	s_nop 0
	global_load_lds_dwordx4 v[146:147], off
	v_lshl_add_u64 v[146:147], v[220:221], 0, s[10:11]
	s_mov_b32 m0, s41
	s_nop 0
	global_load_lds_dwordx4 v[146:147], off
	s_waitcnt vmcnt(8)
	s_waitcnt lgkmcnt(0)
	s_barrier
	s_setprio 1
	s_waitcnt lgkmcnt(0)
	v_mfma_f32_16x16x32_bf16 v[60:63], v[152:155], v[184:187], v[60:63]
	v_mfma_f32_16x16x32_bf16 v[56:59], v[160:163], v[184:187], v[56:59]
	v_mfma_f32_16x16x32_bf16 v[44:47], v[152:155], v[192:195], v[44:47]
	v_mfma_f32_16x16x32_bf16 v[40:43], v[160:163], v[192:195], v[40:43]
	v_mfma_f32_16x16x32_bf16 v[28:31], v[152:155], v[200:203], v[28:31]
	v_mfma_f32_16x16x32_bf16 v[24:27], v[160:163], v[200:203], v[24:27]
	v_mfma_f32_16x16x32_bf16 v[12:15], v[152:155], v[208:211], v[12:15]
	v_mfma_f32_16x16x32_bf16 v[8:11], v[160:163], v[208:211], v[8:11]
	v_mfma_f32_16x16x32_bf16 v[60:63], v[156:159], v[188:191], v[60:63]
	v_mfma_f32_16x16x32_bf16 v[56:59], v[164:167], v[188:191], v[56:59]
	v_mfma_f32_16x16x32_bf16 v[44:47], v[156:159], v[196:199], v[44:47]
	v_mfma_f32_16x16x32_bf16 v[40:43], v[164:167], v[196:199], v[40:43]
	v_mfma_f32_16x16x32_bf16 v[28:31], v[156:159], v[204:207], v[28:31]
	v_mfma_f32_16x16x32_bf16 v[24:27], v[164:167], v[204:207], v[24:27]
	v_mfma_f32_16x16x32_bf16 v[12:15], v[156:159], v[212:215], v[12:15]
	v_mfma_f32_16x16x32_bf16 v[8:11], v[164:167], v[212:215], v[8:11]
	s_setprio 0
	s_setprio 1
	v_mfma_f32_16x16x32_bf16 v[52:55], v[168:171], v[184:187], v[52:55]
	v_mfma_f32_16x16x32_bf16 v[48:51], v[176:179], v[184:187], v[48:51]
	v_mfma_f32_16x16x32_bf16 v[36:39], v[168:171], v[192:195], v[36:39]
	v_mfma_f32_16x16x32_bf16 v[32:35], v[176:179], v[192:195], v[32:35]
	v_mfma_f32_16x16x32_bf16 v[20:23], v[168:171], v[200:203], v[20:23]
	v_mfma_f32_16x16x32_bf16 v[16:19], v[176:179], v[200:203], v[16:19]
	v_mfma_f32_16x16x32_bf16 v[4:7], v[168:171], v[208:211], v[4:7]
	v_mfma_f32_16x16x32_bf16 v[0:3], v[176:179], v[208:211], v[0:3]
	v_mfma_f32_16x16x32_bf16 v[52:55], v[172:175], v[188:191], v[52:55]
	v_mfma_f32_16x16x32_bf16 v[48:51], v[180:183], v[188:191], v[48:51]
	v_mfma_f32_16x16x32_bf16 v[36:39], v[172:175], v[196:199], v[36:39]
	v_mfma_f32_16x16x32_bf16 v[32:35], v[180:183], v[196:199], v[32:35]
	v_mfma_f32_16x16x32_bf16 v[20:23], v[172:175], v[204:207], v[20:23]
	v_mfma_f32_16x16x32_bf16 v[16:19], v[180:183], v[204:207], v[16:19]
	v_mfma_f32_16x16x32_bf16 v[4:7], v[172:175], v[212:215], v[4:7]
	v_mfma_f32_16x16x32_bf16 v[0:3], v[180:183], v[212:215], v[0:3]
	s_setprio 0
	s_barrier
	s_add_i32 s58, s58, 2
	s_add_u32 s22, s22, 0x100
	s_addc_u32 s23, s23, 0
	s_add_u32 s56, s56, 0x100
	s_addc_u32 s57, s57, 0
	s_cmp_gt_u32 s58, 13

.LBB6_19:
	s_ashr_i32 s17, s16, 31
	s_lshl_b64 s[18:19], s[16:17], 21
	s_add_u32 s18, s33, s18
	v_cmp_lt_i64_e64 s[4:5], s[4:5], v[142:143]
	s_addc_u32 s19, s34, s19
	s_and_b64 s[20:21], s[4:5], exec
	s_cselect_b32 s17, s19, s25
	s_cselect_b32 s53, s18, s24
	s_ashr_i32 s15, s14, 31
	s_lshl_b64 s[20:21], s[14:15], 21
	s_add_u32 s20, s6, s20
	s_addc_u32 s21, s7, s21
	s_and_b64 s[28:29], s[4:5], exec
	s_cselect_b32 s15, s21, s27
	s_cselect_b32 s54, s20, s26
	s_add_u32 s24, s24, 0x100080
	s_addc_u32 s25, s25, 0
	s_add_u32 s55, s26, 0x100
	s_addc_u32 s56, s27, 0
	s_mov_b32 s57, -2
	ds_read_b128 v[152:155], v149
	ds_read_b128 v[156:159], v149 offset:1024
	ds_read_b128 v[160:163], v149 offset:2048
	ds_read_b128 v[164:167], v149 offset:3072
	ds_read_b128 v[168:171], v150
	ds_read_b128 v[172:175], v150 offset:1024
	ds_read_b128 v[176:179], v150 offset:2048
	ds_read_b128 v[180:183], v150 offset:3072
	s_add_u32 s26, s24, 0xfff00080
	s_addc_u32 s27, s25, -1
	s_cmp_eq_u32 s57, 60
	s_cselect_b32 s29, s17, s27
	s_cselect_b32 s28, s53, s26
	s_cselect_b32 s27, s15, s56
	s_cselect_b32 s26, s54, s55
	v_lshl_add_u64 v[146:147], s[24:25], 0, v[138:139]
	s_add_i32 m0, s23, 0xc000
	ds_read_b128 v[184:187], v151
	ds_read_b128 v[188:191], v151 offset:1024
	ds_read_b128 v[192:195], v151 offset:2048
	ds_read_b128 v[196:199], v151 offset:3072
	ds_read_b128 v[200:203], v151 offset:4096
	ds_read_b128 v[204:207], v151 offset:5120
	ds_read_b128 v[208:211], v151 offset:6144
	ds_read_b128 v[212:215], v151 offset:7168
	global_load_lds_dwordx4 v[146:147], off
	v_lshl_add_u64 v[146:147], s[24:25], 0, v[140:141]
	s_add_i32 m0, s23, 0xe000
	s_nop 0
	global_load_lds_dwordx4 v[146:147], off
	s_waitcnt vmcnt(8)
	s_waitcnt lgkmcnt(0)
	s_barrier
	s_setprio 1
	s_waitcnt lgkmcnt(0)
	v_mfma_f32_16x16x32_bf16 v[124:127], v[152:155], v[184:187], 0
	v_mfma_f32_16x16x32_bf16 v[120:123], v[160:163], v[184:187], 0
	v_mfma_f32_16x16x32_bf16 v[116:119], v[152:155], v[192:195], 0
	v_mfma_f32_16x16x32_bf16 v[108:111], v[160:163], v[192:195], 0
	v_mfma_f32_16x16x32_bf16 v[100:103], v[152:155], v[200:203], 0
	v_mfma_f32_16x16x32_bf16 v[92:95], v[160:163], v[200:203], 0
	v_mfma_f32_16x16x32_bf16 v[84:87], v[152:155], v[208:211], 0
	v_mfma_f32_16x16x32_bf16 v[76:79], v[160:163], v[208:211], 0
	v_mfma_f32_16x16x32_bf16 v[124:127], v[156:159], v[188:191], v[124:127]
	v_mfma_f32_16x16x32_bf16 v[120:123], v[164:167], v[188:191], v[120:123]
	v_mfma_f32_16x16x32_bf16 v[116:119], v[156:159], v[196:199], v[116:119]
	v_mfma_f32_16x16x32_bf16 v[108:111], v[164:167], v[196:199], v[108:111]
	v_mfma_f32_16x16x32_bf16 v[100:103], v[156:159], v[204:207], v[100:103]
	v_mfma_f32_16x16x32_bf16 v[92:95], v[164:167], v[204:207], v[92:95]
	v_mfma_f32_16x16x32_bf16 v[84:87], v[156:159], v[212:215], v[84:87]
	v_mfma_f32_16x16x32_bf16 v[76:79], v[164:167], v[212:215], v[76:79]
	s_setprio 0
	s_setprio 1
	v_mfma_f32_16x16x32_bf16 v[112:115], v[168:171], v[184:187], 0
	v_mfma_f32_16x16x32_bf16 v[104:107], v[176:179], v[184:187], 0
	v_mfma_f32_16x16x32_bf16 v[96:99], v[168:171], v[192:195], 0
	v_mfma_f32_16x16x32_bf16 v[88:91], v[176:179], v[192:195], 0
	v_mfma_f32_16x16x32_bf16 v[80:83], v[168:171], v[200:203], 0
	v_mfma_f32_16x16x32_bf16 v[72:75], v[176:179], v[200:203], 0
	v_mfma_f32_16x16x32_bf16 v[68:71], v[168:171], v[208:211], 0
	v_mfma_f32_16x16x32_bf16 v[64:67], v[176:179], v[208:211], 0
	v_mfma_f32_16x16x32_bf16 v[112:115], v[172:175], v[188:191], v[112:115]
	v_mfma_f32_16x16x32_bf16 v[104:107], v[180:183], v[188:191], v[104:107]
	v_mfma_f32_16x16x32_bf16 v[96:99], v[172:175], v[196:199], v[96:99]
	v_mfma_f32_16x16x32_bf16 v[88:91], v[180:183], v[196:199], v[88:91]
	v_mfma_f32_16x16x32_bf16 v[80:83], v[172:175], v[204:207], v[80:83]
	v_mfma_f32_16x16x32_bf16 v[72:75], v[180:183], v[204:207], v[72:75]
	v_mfma_f32_16x16x32_bf16 v[68:71], v[172:175], v[212:215], v[68:71]
	v_mfma_f32_16x16x32_bf16 v[64:67], v[180:183], v[212:215], v[64:67]
	s_setprio 0
	s_barrier
	s_add_i32 s58, s45, s31
	v_lshl_add_u64 v[146:147], s[26:27], 0, v[130:131]
	s_mov_b32 m0, s58
	ds_read_b128 v[184:187], v151 offset:16384
	ds_read_b128 v[188:191], v151 offset:17408
	ds_read_b128 v[192:195], v151 offset:18432
	ds_read_b128 v[196:199], v151 offset:19456
	ds_read_b128 v[200:203], v151 offset:20480
	ds_read_b128 v[204:207], v151 offset:21504
	ds_read_b128 v[208:211], v151 offset:22528
	ds_read_b128 v[212:215], v151 offset:23552
	global_load_lds_dwordx4 v[146:147], off
	s_add_i32 m0, s58, 0x2000
	s_add_u32 s58, s26, 0x100000
	v_lshl_add_u64 v[216:217], s[26:27], 0, v[134:135]
	s_addc_u32 s59, s27, 0
	s_add_i32 s60, s46, s31
	global_load_lds_dwordx4 v[216:217], off
	v_lshl_add_u64 v[218:219], s[58:59], 0, v[130:131]
	s_mov_b32 m0, s60
	v_lshl_add_u64 v[220:221], s[28:29], 0, v[132:133]
	global_load_lds_dwordx4 v[218:219], off
	v_lshl_add_u64 v[218:219], s[58:59], 0, v[134:135]
	s_add_i32 m0, s60, 0x2000
	s_nop 0
	global_load_lds_dwordx4 v[218:219], off
	v_lshl_add_u64 v[218:219], s[28:29], 0, v[128:129]
	s_mov_b32 m0, s23
	s_nop 0
	global_load_lds_dwordx4 v[218:219], off
	s_mov_b32 m0, s35
	s_nop 0
	global_load_lds_dwordx4 v[220:221], off
	s_waitcnt vmcnt(8)
	s_waitcnt lgkmcnt(0)
	s_barrier
	s_setprio 1
	s_waitcnt lgkmcnt(0)
	v_mfma_f32_16x16x32_bf16 v[60:63], v[152:155], v[184:187], 0
	v_mfma_f32_16x16x32_bf16 v[56:59], v[160:163], v[184:187], 0
	v_mfma_f32_16x16x32_bf16 v[52:55], v[152:155], v[192:195], 0
	v_mfma_f32_16x16x32_bf16 v[44:47], v[160:163], v[192:195], 0
	v_mfma_f32_16x16x32_bf16 v[36:39], v[152:155], v[200:203], 0
	v_mfma_f32_16x16x32_bf16 v[28:31], v[160:163], v[200:203], 0
	v_mfma_f32_16x16x32_bf16 v[20:23], v[152:155], v[208:211], 0
	v_mfma_f32_16x16x32_bf16 v[12:15], v[160:163], v[208:211], 0
	v_mfma_f32_16x16x32_bf16 v[60:63], v[156:159], v[188:191], v[60:63]
	v_mfma_f32_16x16x32_bf16 v[56:59], v[164:167], v[188:191], v[56:59]
	v_mfma_f32_16x16x32_bf16 v[52:55], v[156:159], v[196:199], v[52:55]
	v_mfma_f32_16x16x32_bf16 v[44:47], v[164:167], v[196:199], v[44:47]
	v_mfma_f32_16x16x32_bf16 v[36:39], v[156:159], v[204:207], v[36:39]
	v_mfma_f32_16x16x32_bf16 v[28:31], v[164:167], v[204:207], v[28:31]
	v_mfma_f32_16x16x32_bf16 v[20:23], v[156:159], v[212:215], v[20:23]
	v_mfma_f32_16x16x32_bf16 v[12:15], v[164:167], v[212:215], v[12:15]
	s_setprio 0
	s_setprio 1
	v_mfma_f32_16x16x32_bf16 v[48:51], v[168:171], v[184:187], 0
	v_mfma_f32_16x16x32_bf16 v[40:43], v[176:179], v[184:187], 0
	v_mfma_f32_16x16x32_bf16 v[32:35], v[168:171], v[192:195], 0
	v_mfma_f32_16x16x32_bf16 v[24:27], v[176:179], v[192:195], 0
	v_mfma_f32_16x16x32_bf16 v[16:19], v[168:171], v[200:203], 0
	v_mfma_f32_16x16x32_bf16 v[8:11], v[176:179], v[200:203], 0
	v_mfma_f32_16x16x32_bf16 v[4:7], v[168:171], v[208:211], 0
	v_mfma_f32_16x16x32_bf16 v[0:3], v[176:179], v[208:211], 0
	v_mfma_f32_16x16x32_bf16 v[48:51], v[172:175], v[188:191], v[48:51]
	v_mfma_f32_16x16x32_bf16 v[40:43], v[180:183], v[188:191], v[40:43]
	v_mfma_f32_16x16x32_bf16 v[32:35], v[172:175], v[196:199], v[32:35]
	v_mfma_f32_16x16x32_bf16 v[24:27], v[180:183], v[196:199], v[24:27]
	v_mfma_f32_16x16x32_bf16 v[16:19], v[172:175], v[204:207], v[16:19]
	v_mfma_f32_16x16x32_bf16 v[8:11], v[180:183], v[204:207], v[8:11]
	v_mfma_f32_16x16x32_bf16 v[4:7], v[172:175], v[212:215], v[4:7]
	v_mfma_f32_16x16x32_bf16 v[0:3], v[180:183], v[212:215], v[0:3]
	s_setprio 0
	s_barrier
	s_add_i32 s58, 0, 0x18000
	s_add_i32 s59, 0, 0x1c000
	v_add_u32_e32 v164, s58, v148
	v_add_u32_e32 v180, s59, v148
	ds_read_b128 v[152:155], v164
	ds_read_b128 v[156:159], v164 offset:1024
	ds_read_b128 v[160:163], v164 offset:2048
	ds_read_b128 v[164:167], v164 offset:3072
	ds_read_b128 v[168:171], v180
	ds_read_b128 v[172:175], v180 offset:1024
	ds_read_b128 v[176:179], v180 offset:2048
	ds_read_b128 v[180:183], v180 offset:3072
	s_add_u32 s28, s28, 0x100000
	s_addc_u32 s29, s29, 0
	s_mov_b32 m0, s36
	v_lshl_add_u64 v[222:223], s[28:29], 0, v[128:129]
	ds_read_b128 v[184:187], v151 offset:32768
	ds_read_b128 v[188:191], v151 offset:33792
	ds_read_b128 v[192:195], v151 offset:34816
	ds_read_b128 v[196:199], v151 offset:35840
	ds_read_b128 v[200:203], v151 offset:36864
	ds_read_b128 v[204:207], v151 offset:37888
	ds_read_b128 v[208:211], v151 offset:38912
	ds_read_b128 v[212:215], v151 offset:39936
	global_load_lds_dwordx4 v[222:223], off
	v_lshl_add_u64 v[222:223], s[28:29], 0, v[132:133]
	s_mov_b32 m0, s37
	s_nop 0
	global_load_lds_dwordx4 v[222:223], off
	s_waitcnt vmcnt(8)
	s_waitcnt lgkmcnt(0)
	s_barrier
	s_setprio 1
	s_waitcnt lgkmcnt(0)
	v_mfma_f32_16x16x32_bf16 v[124:127], v[152:155], v[184:187], v[124:127]
	v_mfma_f32_16x16x32_bf16 v[120:123], v[160:163], v[184:187], v[120:123]
	v_mfma_f32_16x16x32_bf16 v[116:119], v[152:155], v[192:195], v[116:119]
	v_mfma_f32_16x16x32_bf16 v[108:111], v[160:163], v[192:195], v[108:111]
	v_mfma_f32_16x16x32_bf16 v[100:103], v[152:155], v[200:203], v[100:103]
	v_mfma_f32_16x16x32_bf16 v[92:95], v[160:163], v[200:203], v[92:95]
	v_mfma_f32_16x16x32_bf16 v[84:87], v[152:155], v[208:211], v[84:87]
	v_mfma_f32_16x16x32_bf16 v[76:79], v[160:163], v[208:211], v[76:79]
	v_mfma_f32_16x16x32_bf16 v[124:127], v[156:159], v[188:191], v[124:127]
	v_mfma_f32_16x16x32_bf16 v[120:123], v[164:167], v[188:191], v[120:123]
	v_mfma_f32_16x16x32_bf16 v[116:119], v[156:159], v[196:199], v[116:119]
	v_mfma_f32_16x16x32_bf16 v[108:111], v[164:167], v[196:199], v[108:111]
	v_mfma_f32_16x16x32_bf16 v[100:103], v[156:159], v[204:207], v[100:103]
	v_mfma_f32_16x16x32_bf16 v[92:95], v[164:167], v[204:207], v[92:95]
	v_mfma_f32_16x16x32_bf16 v[84:87], v[156:159], v[212:215], v[84:87]
	v_mfma_f32_16x16x32_bf16 v[76:79], v[164:167], v[212:215], v[76:79]
	s_setprio 0
	s_setprio 1
	v_mfma_f32_16x16x32_bf16 v[112:115], v[168:171], v[184:187], v[112:115]
	v_mfma_f32_16x16x32_bf16 v[104:107], v[176:179], v[184:187], v[104:107]
	v_mfma_f32_16x16x32_bf16 v[96:99], v[168:171], v[192:195], v[96:99]
	v_mfma_f32_16x16x32_bf16 v[88:91], v[176:179], v[192:195], v[88:91]
	v_mfma_f32_16x16x32_bf16 v[80:83], v[168:171], v[200:203], v[80:83]
	v_mfma_f32_16x16x32_bf16 v[72:75], v[176:179], v[200:203], v[72:75]
	v_mfma_f32_16x16x32_bf16 v[68:71], v[168:171], v[208:211], v[68:71]
	v_mfma_f32_16x16x32_bf16 v[64:67], v[176:179], v[208:211], v[64:67]
	v_mfma_f32_16x16x32_bf16 v[112:115], v[172:175], v[188:191], v[112:115]
	v_mfma_f32_16x16x32_bf16 v[104:107], v[180:183], v[188:191], v[104:107]
	v_mfma_f32_16x16x32_bf16 v[96:99], v[172:175], v[196:199], v[96:99]
	v_mfma_f32_16x16x32_bf16 v[88:91], v[180:183], v[196:199], v[88:91]
	v_mfma_f32_16x16x32_bf16 v[80:83], v[172:175], v[204:207], v[80:83]
	v_mfma_f32_16x16x32_bf16 v[72:75], v[180:183], v[204:207], v[72:75]
	v_mfma_f32_16x16x32_bf16 v[68:71], v[172:175], v[212:215], v[68:71]
	v_mfma_f32_16x16x32_bf16 v[64:67], v[180:183], v[212:215], v[64:67]
	s_setprio 0
	s_barrier
	s_add_i32 s28, s58, s31
	v_lshl_add_u64 v[146:147], v[146:147], 0, s[12:13]
	s_mov_b32 m0, s28
	ds_read_b128 v[184:187], v151 offset:49152
	ds_read_b128 v[188:191], v151 offset:50176
	ds_read_b128 v[192:195], v151 offset:51200
	ds_read_b128 v[196:199], v151 offset:52224
	ds_read_b128 v[200:203], v151 offset:53248
	ds_read_b128 v[204:207], v151 offset:54272
	ds_read_b128 v[208:211], v151 offset:55296
	ds_read_b128 v[212:215], v151 offset:56320
	global_load_lds_dwordx4 v[146:147], off
	s_add_i32 m0, s28, 0x2000
	s_add_u32 s26, s26, 0x100080
	v_lshl_add_u64 v[146:147], v[216:217], 0, s[12:13]
	s_addc_u32 s27, s27, 0
	s_add_i32 s28, s59, s31
	global_load_lds_dwordx4 v[146:147], off
	v_lshl_add_u64 v[146:147], s[26:27], 0, v[130:131]
	s_mov_b32 m0, s28
	s_nop 0
	global_load_lds_dwordx4 v[146:147], off
	v_lshl_add_u64 v[146:147], s[26:27], 0, v[134:135]
	s_add_i32 m0, s28, 0x2000
	s_nop 0
	global_load_lds_dwordx4 v[146:147], off
	v_lshl_add_u64 v[146:147], v[218:219], 0, s[12:13]
	s_mov_b32 m0, s40
	s_nop 0
	global_load_lds_dwordx4 v[146:147], off
	v_lshl_add_u64 v[146:147], v[220:221], 0, s[12:13]
	s_mov_b32 m0, s41
	s_nop 0
	global_load_lds_dwordx4 v[146:147], off
	s_waitcnt vmcnt(8)
	s_waitcnt lgkmcnt(0)
	s_barrier
	s_setprio 1
	s_waitcnt lgkmcnt(0)
	v_mfma_f32_16x16x32_bf16 v[60:63], v[152:155], v[184:187], v[60:63]
	v_mfma_f32_16x16x32_bf16 v[56:59], v[160:163], v[184:187], v[56:59]
	v_mfma_f32_16x16x32_bf16 v[52:55], v[152:155], v[192:195], v[52:55]
	v_mfma_f32_16x16x32_bf16 v[44:47], v[160:163], v[192:195], v[44:47]
	v_mfma_f32_16x16x32_bf16 v[36:39], v[152:155], v[200:203], v[36:39]
	v_mfma_f32_16x16x32_bf16 v[28:31], v[160:163], v[200:203], v[28:31]
	v_mfma_f32_16x16x32_bf16 v[20:23], v[152:155], v[208:211], v[20:23]
	v_mfma_f32_16x16x32_bf16 v[12:15], v[160:163], v[208:211], v[12:15]
	v_mfma_f32_16x16x32_bf16 v[60:63], v[156:159], v[188:191], v[60:63]
	v_mfma_f32_16x16x32_bf16 v[56:59], v[164:167], v[188:191], v[56:59]
	v_mfma_f32_16x16x32_bf16 v[52:55], v[156:159], v[196:199], v[52:55]
	v_mfma_f32_16x16x32_bf16 v[44:47], v[164:167], v[196:199], v[44:47]
	v_mfma_f32_16x16x32_bf16 v[36:39], v[156:159], v[204:207], v[36:39]
	v_mfma_f32_16x16x32_bf16 v[28:31], v[164:167], v[204:207], v[28:31]
	v_mfma_f32_16x16x32_bf16 v[20:23], v[156:159], v[212:215], v[20:23]
	v_mfma_f32_16x16x32_bf16 v[12:15], v[164:167], v[212:215], v[12:15]
	s_setprio 0
	s_setprio 1
	v_mfma_f32_16x16x32_bf16 v[48:51], v[168:171], v[184:187], v[48:51]
	v_mfma_f32_16x16x32_bf16 v[40:43], v[176:179], v[184:187], v[40:43]
	v_mfma_f32_16x16x32_bf16 v[32:35], v[168:171], v[192:195], v[32:35]
	v_mfma_f32_16x16x32_bf16 v[24:27], v[176:179], v[192:195], v[24:27]
	v_mfma_f32_16x16x32_bf16 v[16:19], v[168:171], v[200:203], v[16:19]
	v_mfma_f32_16x16x32_bf16 v[8:11], v[176:179], v[200:203], v[8:11]
	v_mfma_f32_16x16x32_bf16 v[4:7], v[168:171], v[208:211], v[4:7]
	v_mfma_f32_16x16x32_bf16 v[0:3], v[176:179], v[208:211], v[0:3]
	v_mfma_f32_16x16x32_bf16 v[48:51], v[172:175], v[188:191], v[48:51]
	v_mfma_f32_16x16x32_bf16 v[40:43], v[180:183], v[188:191], v[40:43]
	v_mfma_f32_16x16x32_bf16 v[32:35], v[172:175], v[196:199], v[32:35]
	v_mfma_f32_16x16x32_bf16 v[24:27], v[180:183], v[196:199], v[24:27]
	v_mfma_f32_16x16x32_bf16 v[16:19], v[172:175], v[204:207], v[16:19]
	v_mfma_f32_16x16x32_bf16 v[8:11], v[180:183], v[204:207], v[8:11]
	v_mfma_f32_16x16x32_bf16 v[4:7], v[172:175], v[212:215], v[4:7]
	v_mfma_f32_16x16x32_bf16 v[0:3], v[180:183], v[212:215], v[0:3]
	s_setprio 0
	s_barrier
	s_add_i32 s57, s57, 2
	s_add_u32 s24, s24, 0x100
	s_addc_u32 s25, s25, 0
	s_add_u32 s55, s55, 0x100
	s_addc_u32 s56, s56, 0
	s_cmp_gt_u32 s57, 61

.LBB8_11:
	s_ashr_i32 s19, s18, 31
	v_cmp_lt_i64_e32 vcc, s[0:1], v[144:145]
	s_lshl_b64 s[0:1], s[18:19], 19
	s_add_u32 s20, s33, s0
	s_addc_u32 s21, s36, s1
	s_and_b64 s[0:1], vcc, exec
	s_cselect_b32 s5, s21, s29
	s_cselect_b32 s19, s20, s28
	s_ashr_i32 s11, s10, 31
	s_lshl_b64 s[0:1], s[10:11], 19
	s_add_u32 s22, s37, s0
	s_addc_u32 s23, s38, s1
	s_and_b64 s[0:1], vcc, exec
	s_cselect_b32 s11, s23, s27
	s_cselect_b32 s25, s22, s26
	s_add_u32 s34, s26, 0x100
	s_addc_u32 s35, s27, 0
	s_add_u32 s26, s28, 0x40080
	s_addc_u32 s27, s29, 0
	s_mov_b32 s65, -2
	ds_read_b128 v[148:151], v153
	ds_read_b128 v[156:159], v153 offset:1024
	ds_read_b128 v[160:163], v153 offset:2048
	ds_read_b128 v[164:167], v153 offset:3072
	ds_read_b128 v[168:171], v154
	ds_read_b128 v[172:175], v154 offset:1024
	ds_read_b128 v[176:179], v154 offset:2048
	ds_read_b128 v[180:183], v154 offset:3072
	s_add_u32 s28, s26, 0xfffc0080
	s_addc_u32 s29, s27, -1
	s_cmp_eq_u32 s65, 12
	s_cselect_b32 s31, s5, s29
	s_cselect_b32 s30, s19, s28
	s_cselect_b32 s29, s11, s35
	s_cselect_b32 s28, s25, s34
	v_lshl_add_u64 v[216:217], s[26:27], 0, v[142:143]
	s_add_i32 m0, s40, 0xc000
	ds_read_b128 v[184:187], v155
	ds_read_b128 v[188:191], v155 offset:1024
	ds_read_b128 v[192:195], v155 offset:2048
	ds_read_b128 v[196:199], v155 offset:3072
	ds_read_b128 v[200:203], v155 offset:4096
	ds_read_b128 v[204:207], v155 offset:5120
	ds_read_b128 v[208:211], v155 offset:6144
	ds_read_b128 v[212:215], v155 offset:7168
	global_load_lds_dwordx4 v[216:217], off
	v_lshl_add_u64 v[216:217], s[26:27], 0, v[140:141]
	s_add_i32 m0, s40, 0xe000
	s_nop 0
	global_load_lds_dwordx4 v[216:217], off
	s_waitcnt vmcnt(8)
	s_waitcnt lgkmcnt(0)
	s_barrier
	s_setprio 1
	s_waitcnt lgkmcnt(0)
	v_mfma_f32_16x16x32_bf16 v[124:127], v[148:151], v[184:187], 0
	v_mfma_f32_16x16x32_bf16 v[120:123], v[160:163], v[184:187], 0
	v_mfma_f32_16x16x32_bf16 v[108:111], v[148:151], v[192:195], 0
	v_mfma_f32_16x16x32_bf16 v[104:107], v[160:163], v[192:195], 0
	v_mfma_f32_16x16x32_bf16 v[92:95], v[148:151], v[200:203], 0
	v_mfma_f32_16x16x32_bf16 v[88:91], v[160:163], v[200:203], 0
	v_mfma_f32_16x16x32_bf16 v[76:79], v[148:151], v[208:211], 0
	v_mfma_f32_16x16x32_bf16 v[72:75], v[160:163], v[208:211], 0
	v_mfma_f32_16x16x32_bf16 v[124:127], v[156:159], v[188:191], v[124:127]
	v_mfma_f32_16x16x32_bf16 v[120:123], v[164:167], v[188:191], v[120:123]
	v_mfma_f32_16x16x32_bf16 v[108:111], v[156:159], v[196:199], v[108:111]
	v_mfma_f32_16x16x32_bf16 v[104:107], v[164:167], v[196:199], v[104:107]
	v_mfma_f32_16x16x32_bf16 v[92:95], v[156:159], v[204:207], v[92:95]
	v_mfma_f32_16x16x32_bf16 v[88:91], v[164:167], v[204:207], v[88:91]
	v_mfma_f32_16x16x32_bf16 v[76:79], v[156:159], v[212:215], v[76:79]
	v_mfma_f32_16x16x32_bf16 v[72:75], v[164:167], v[212:215], v[72:75]
	s_setprio 0
	s_setprio 1
	v_mfma_f32_16x16x32_bf16 v[116:119], v[168:171], v[184:187], 0
	v_mfma_f32_16x16x32_bf16 v[112:115], v[176:179], v[184:187], 0
	v_mfma_f32_16x16x32_bf16 v[100:103], v[168:171], v[192:195], 0
	v_mfma_f32_16x16x32_bf16 v[96:99], v[176:179], v[192:195], 0
	v_mfma_f32_16x16x32_bf16 v[84:87], v[168:171], v[200:203], 0
	v_mfma_f32_16x16x32_bf16 v[80:83], v[176:179], v[200:203], 0
	v_mfma_f32_16x16x32_bf16 v[68:71], v[168:171], v[208:211], 0
	v_mfma_f32_16x16x32_bf16 v[64:67], v[176:179], v[208:211], 0
	v_mfma_f32_16x16x32_bf16 v[116:119], v[172:175], v[188:191], v[116:119]
	v_mfma_f32_16x16x32_bf16 v[112:115], v[180:183], v[188:191], v[112:115]
	v_mfma_f32_16x16x32_bf16 v[100:103], v[172:175], v[196:199], v[100:103]
	v_mfma_f32_16x16x32_bf16 v[96:99], v[180:183], v[196:199], v[96:99]
	v_mfma_f32_16x16x32_bf16 v[84:87], v[172:175], v[204:207], v[84:87]
	v_mfma_f32_16x16x32_bf16 v[80:83], v[180:183], v[204:207], v[80:83]
	v_mfma_f32_16x16x32_bf16 v[68:71], v[172:175], v[212:215], v[68:71]
	v_mfma_f32_16x16x32_bf16 v[64:67], v[180:183], v[212:215], v[64:67]
	s_setprio 0
	s_barrier
	s_add_i32 s66, s52, s39
	v_lshl_add_u64 v[216:217], s[28:29], 0, v[130:131]
	s_mov_b32 m0, s66
	ds_read_b128 v[184:187], v155 offset:16384
	ds_read_b128 v[188:191], v155 offset:17408
	ds_read_b128 v[192:195], v155 offset:18432
	ds_read_b128 v[196:199], v155 offset:19456
	ds_read_b128 v[200:203], v155 offset:20480
	ds_read_b128 v[204:207], v155 offset:21504
	ds_read_b128 v[208:211], v155 offset:22528
	ds_read_b128 v[212:215], v155 offset:23552
	global_load_lds_dwordx4 v[216:217], off
	s_add_i32 m0, s66, 0x2000
	s_add_u32 s66, s28, 0x40000
	v_lshl_add_u64 v[218:219], s[28:29], 0, v[134:135]
	s_addc_u32 s67, s29, 0
	s_add_i32 s68, s53, s39
	global_load_lds_dwordx4 v[218:219], off
	v_lshl_add_u64 v[220:221], s[66:67], 0, v[130:131]
	s_mov_b32 m0, s68
	v_lshl_add_u64 v[222:223], s[30:31], 0, v[132:133]
	global_load_lds_dwordx4 v[220:221], off
	v_lshl_add_u64 v[220:221], s[66:67], 0, v[134:135]
	s_add_i32 m0, s68, 0x2000
	s_nop 0
	global_load_lds_dwordx4 v[220:221], off
	v_lshl_add_u64 v[220:221], s[30:31], 0, v[128:129]
	s_mov_b32 m0, s40
	s_nop 0
	global_load_lds_dwordx4 v[220:221], off
	s_mov_b32 m0, s41
	s_nop 0
	global_load_lds_dwordx4 v[222:223], off
	s_waitcnt vmcnt(8)
	s_waitcnt lgkmcnt(0)
	s_barrier
	s_setprio 1
	s_waitcnt lgkmcnt(0)
	v_mfma_f32_16x16x32_bf16 v[60:63], v[148:151], v[184:187], 0
	v_mfma_f32_16x16x32_bf16 v[56:59], v[160:163], v[184:187], 0
	v_mfma_f32_16x16x32_bf16 v[44:47], v[148:151], v[192:195], 0
	v_mfma_f32_16x16x32_bf16 v[40:43], v[160:163], v[192:195], 0
	v_mfma_f32_16x16x32_bf16 v[28:31], v[148:151], v[200:203], 0
	v_mfma_f32_16x16x32_bf16 v[24:27], v[160:163], v[200:203], 0
	v_mfma_f32_16x16x32_bf16 v[12:15], v[148:151], v[208:211], 0
	v_mfma_f32_16x16x32_bf16 v[8:11], v[160:163], v[208:211], 0
	v_mfma_f32_16x16x32_bf16 v[60:63], v[156:159], v[188:191], v[60:63]
	v_mfma_f32_16x16x32_bf16 v[56:59], v[164:167], v[188:191], v[56:59]
	v_mfma_f32_16x16x32_bf16 v[44:47], v[156:159], v[196:199], v[44:47]
	v_mfma_f32_16x16x32_bf16 v[40:43], v[164:167], v[196:199], v[40:43]
	v_mfma_f32_16x16x32_bf16 v[28:31], v[156:159], v[204:207], v[28:31]
	v_mfma_f32_16x16x32_bf16 v[24:27], v[164:167], v[204:207], v[24:27]
	v_mfma_f32_16x16x32_bf16 v[12:15], v[156:159], v[212:215], v[12:15]
	v_mfma_f32_16x16x32_bf16 v[8:11], v[164:167], v[212:215], v[8:11]
	s_setprio 0
	s_setprio 1
	v_mfma_f32_16x16x32_bf16 v[52:55], v[168:171], v[184:187], 0
	v_mfma_f32_16x16x32_bf16 v[48:51], v[176:179], v[184:187], 0
	v_mfma_f32_16x16x32_bf16 v[36:39], v[168:171], v[192:195], 0
	v_mfma_f32_16x16x32_bf16 v[32:35], v[176:179], v[192:195], 0
	v_mfma_f32_16x16x32_bf16 v[20:23], v[168:171], v[200:203], 0
	v_mfma_f32_16x16x32_bf16 v[16:19], v[176:179], v[200:203], 0
	v_mfma_f32_16x16x32_bf16 v[4:7], v[168:171], v[208:211], 0
	v_mfma_f32_16x16x32_bf16 v[0:3], v[176:179], v[208:211], 0
	v_mfma_f32_16x16x32_bf16 v[52:55], v[172:175], v[188:191], v[52:55]
	v_mfma_f32_16x16x32_bf16 v[48:51], v[180:183], v[188:191], v[48:51]
	v_mfma_f32_16x16x32_bf16 v[36:39], v[172:175], v[196:199], v[36:39]
	v_mfma_f32_16x16x32_bf16 v[32:35], v[180:183], v[196:199], v[32:35]
	v_mfma_f32_16x16x32_bf16 v[20:23], v[172:175], v[204:207], v[20:23]
	v_mfma_f32_16x16x32_bf16 v[16:19], v[180:183], v[204:207], v[16:19]
	v_mfma_f32_16x16x32_bf16 v[4:7], v[172:175], v[212:215], v[4:7]
	v_mfma_f32_16x16x32_bf16 v[0:3], v[180:183], v[212:215], v[0:3]
	s_setprio 0
	s_barrier
	s_add_i32 s66, 0, 0x18000
	s_add_i32 s67, 0, 0x1c000
	v_add_u32_e32 v164, s66, v152
	v_add_u32_e32 v180, s67, v152
	ds_read_b128 v[148:151], v164
	ds_read_b128 v[156:159], v164 offset:1024
	ds_read_b128 v[160:163], v164 offset:2048
	ds_read_b128 v[164:167], v164 offset:3072
	ds_read_b128 v[168:171], v180
	ds_read_b128 v[172:175], v180 offset:1024
	ds_read_b128 v[176:179], v180 offset:2048
	ds_read_b128 v[180:183], v180 offset:3072
	s_add_u32 s30, s30, 0x40000
	s_addc_u32 s31, s31, 0
	s_mov_b32 m0, s42
	v_lshl_add_u64 v[224:225], s[30:31], 0, v[128:129]
	ds_read_b128 v[184:187], v155 offset:32768
	ds_read_b128 v[188:191], v155 offset:33792
	ds_read_b128 v[192:195], v155 offset:34816
	ds_read_b128 v[196:199], v155 offset:35840
	ds_read_b128 v[200:203], v155 offset:36864
	ds_read_b128 v[204:207], v155 offset:37888
	ds_read_b128 v[208:211], v155 offset:38912
	ds_read_b128 v[212:215], v155 offset:39936
	global_load_lds_dwordx4 v[224:225], off
	v_lshl_add_u64 v[224:225], s[30:31], 0, v[132:133]
	s_mov_b32 m0, s43
	s_nop 0
	global_load_lds_dwordx4 v[224:225], off
	s_waitcnt vmcnt(8)
	s_waitcnt lgkmcnt(0)
	s_barrier
	s_setprio 1
	s_waitcnt lgkmcnt(0)
	v_mfma_f32_16x16x32_bf16 v[124:127], v[148:151], v[184:187], v[124:127]
	v_mfma_f32_16x16x32_bf16 v[120:123], v[160:163], v[184:187], v[120:123]
	v_mfma_f32_16x16x32_bf16 v[108:111], v[148:151], v[192:195], v[108:111]
	v_mfma_f32_16x16x32_bf16 v[104:107], v[160:163], v[192:195], v[104:107]
	v_mfma_f32_16x16x32_bf16 v[92:95], v[148:151], v[200:203], v[92:95]
	v_mfma_f32_16x16x32_bf16 v[88:91], v[160:163], v[200:203], v[88:91]
	v_mfma_f32_16x16x32_bf16 v[76:79], v[148:151], v[208:211], v[76:79]
	v_mfma_f32_16x16x32_bf16 v[72:75], v[160:163], v[208:211], v[72:75]
	v_mfma_f32_16x16x32_bf16 v[124:127], v[156:159], v[188:191], v[124:127]
	v_mfma_f32_16x16x32_bf16 v[120:123], v[164:167], v[188:191], v[120:123]
	v_mfma_f32_16x16x32_bf16 v[108:111], v[156:159], v[196:199], v[108:111]
	v_mfma_f32_16x16x32_bf16 v[104:107], v[164:167], v[196:199], v[104:107]
	v_mfma_f32_16x16x32_bf16 v[92:95], v[156:159], v[204:207], v[92:95]
	v_mfma_f32_16x16x32_bf16 v[88:91], v[164:167], v[204:207], v[88:91]
	v_mfma_f32_16x16x32_bf16 v[76:79], v[156:159], v[212:215], v[76:79]
	v_mfma_f32_16x16x32_bf16 v[72:75], v[164:167], v[212:215], v[72:75]
	s_setprio 0
	s_setprio 1
	v_mfma_f32_16x16x32_bf16 v[116:119], v[168:171], v[184:187], v[116:119]
	v_mfma_f32_16x16x32_bf16 v[112:115], v[176:179], v[184:187], v[112:115]
	v_mfma_f32_16x16x32_bf16 v[100:103], v[168:171], v[192:195], v[100:103]
	v_mfma_f32_16x16x32_bf16 v[96:99], v[176:179], v[192:195], v[96:99]
	v_mfma_f32_16x16x32_bf16 v[84:87], v[168:171], v[200:203], v[84:87]
	v_mfma_f32_16x16x32_bf16 v[80:83], v[176:179], v[200:203], v[80:83]
	v_mfma_f32_16x16x32_bf16 v[68:71], v[168:171], v[208:211], v[68:71]
	v_mfma_f32_16x16x32_bf16 v[64:67], v[176:179], v[208:211], v[64:67]
	v_mfma_f32_16x16x32_bf16 v[116:119], v[172:175], v[188:191], v[116:119]
	v_mfma_f32_16x16x32_bf16 v[112:115], v[180:183], v[188:191], v[112:115]
	v_mfma_f32_16x16x32_bf16 v[100:103], v[172:175], v[196:199], v[100:103]
	v_mfma_f32_16x16x32_bf16 v[96:99], v[180:183], v[196:199], v[96:99]
	v_mfma_f32_16x16x32_bf16 v[84:87], v[172:175], v[204:207], v[84:87]
	v_mfma_f32_16x16x32_bf16 v[80:83], v[180:183], v[204:207], v[80:83]
	v_mfma_f32_16x16x32_bf16 v[68:71], v[172:175], v[212:215], v[68:71]
	v_mfma_f32_16x16x32_bf16 v[64:67], v[180:183], v[212:215], v[64:67]
	s_setprio 0
	s_barrier
	s_add_i32 s30, s66, s39
	v_lshl_add_u64 v[216:217], v[216:217], 0, s[14:15]
	s_mov_b32 m0, s30
	ds_read_b128 v[184:187], v155 offset:49152
	ds_read_b128 v[188:191], v155 offset:50176
	ds_read_b128 v[192:195], v155 offset:51200
	ds_read_b128 v[196:199], v155 offset:52224
	ds_read_b128 v[200:203], v155 offset:53248
	ds_read_b128 v[204:207], v155 offset:54272
	ds_read_b128 v[208:211], v155 offset:55296
	ds_read_b128 v[212:215], v155 offset:56320
	global_load_lds_dwordx4 v[216:217], off
	s_add_i32 m0, s30, 0x2000
	s_add_u32 s28, s28, 0x40080
	v_lshl_add_u64 v[216:217], v[218:219], 0, s[14:15]
	s_addc_u32 s29, s29, 0
	s_add_i32 s30, s67, s39
	global_load_lds_dwordx4 v[216:217], off
	v_lshl_add_u64 v[216:217], s[28:29], 0, v[130:131]
	s_mov_b32 m0, s30
	s_nop 0
	global_load_lds_dwordx4 v[216:217], off
	v_lshl_add_u64 v[216:217], s[28:29], 0, v[134:135]
	s_add_i32 m0, s30, 0x2000
	s_nop 0
	global_load_lds_dwordx4 v[216:217], off
	v_lshl_add_u64 v[216:217], v[220:221], 0, s[14:15]
	s_mov_b32 m0, s45
	s_nop 0
	global_load_lds_dwordx4 v[216:217], off
	v_lshl_add_u64 v[216:217], v[222:223], 0, s[14:15]
	s_mov_b32 m0, s46
	s_nop 0
	global_load_lds_dwordx4 v[216:217], off
	s_waitcnt vmcnt(8)
	s_waitcnt lgkmcnt(0)
	s_barrier
	s_setprio 1
	s_waitcnt lgkmcnt(0)
	v_mfma_f32_16x16x32_bf16 v[60:63], v[148:151], v[184:187], v[60:63]
	v_mfma_f32_16x16x32_bf16 v[56:59], v[160:163], v[184:187], v[56:59]
	v_mfma_f32_16x16x32_bf16 v[44:47], v[148:151], v[192:195], v[44:47]
	v_mfma_f32_16x16x32_bf16 v[40:43], v[160:163], v[192:195], v[40:43]
	v_mfma_f32_16x16x32_bf16 v[28:31], v[148:151], v[200:203], v[28:31]
	v_mfma_f32_16x16x32_bf16 v[24:27], v[160:163], v[200:203], v[24:27]
	v_mfma_f32_16x16x32_bf16 v[12:15], v[148:151], v[208:211], v[12:15]
	v_mfma_f32_16x16x32_bf16 v[8:11], v[160:163], v[208:211], v[8:11]
	v_mfma_f32_16x16x32_bf16 v[60:63], v[156:159], v[188:191], v[60:63]
	v_mfma_f32_16x16x32_bf16 v[56:59], v[164:167], v[188:191], v[56:59]
	v_mfma_f32_16x16x32_bf16 v[44:47], v[156:159], v[196:199], v[44:47]
	v_mfma_f32_16x16x32_bf16 v[40:43], v[164:167], v[196:199], v[40:43]
	v_mfma_f32_16x16x32_bf16 v[28:31], v[156:159], v[204:207], v[28:31]
	v_mfma_f32_16x16x32_bf16 v[24:27], v[164:167], v[204:207], v[24:27]
	v_mfma_f32_16x16x32_bf16 v[12:15], v[156:159], v[212:215], v[12:15]
	v_mfma_f32_16x16x32_bf16 v[8:11], v[164:167], v[212:215], v[8:11]
	s_setprio 0
	s_setprio 1
	v_mfma_f32_16x16x32_bf16 v[52:55], v[168:171], v[184:187], v[52:55]
	v_mfma_f32_16x16x32_bf16 v[48:51], v[176:179], v[184:187], v[48:51]
	v_mfma_f32_16x16x32_bf16 v[36:39], v[168:171], v[192:195], v[36:39]
	v_mfma_f32_16x16x32_bf16 v[32:35], v[176:179], v[192:195], v[32:35]
	v_mfma_f32_16x16x32_bf16 v[20:23], v[168:171], v[200:203], v[20:23]
	v_mfma_f32_16x16x32_bf16 v[16:19], v[176:179], v[200:203], v[16:19]
	v_mfma_f32_16x16x32_bf16 v[4:7], v[168:171], v[208:211], v[4:7]
	v_mfma_f32_16x16x32_bf16 v[0:3], v[176:179], v[208:211], v[0:3]
	v_mfma_f32_16x16x32_bf16 v[52:55], v[172:175], v[188:191], v[52:55]
	v_mfma_f32_16x16x32_bf16 v[48:51], v[180:183], v[188:191], v[48:51]
	v_mfma_f32_16x16x32_bf16 v[36:39], v[172:175], v[196:199], v[36:39]
	v_mfma_f32_16x16x32_bf16 v[32:35], v[180:183], v[196:199], v[32:35]
	v_mfma_f32_16x16x32_bf16 v[20:23], v[172:175], v[204:207], v[20:23]
	v_mfma_f32_16x16x32_bf16 v[16:19], v[180:183], v[204:207], v[16:19]
	v_mfma_f32_16x16x32_bf16 v[4:7], v[172:175], v[212:215], v[4:7]
	v_mfma_f32_16x16x32_bf16 v[0:3], v[180:183], v[212:215], v[0:3]
	s_setprio 0
	s_barrier
	s_add_i32 s65, s65, 2
	s_add_u32 s34, s34, 0x100
	s_addc_u32 s35, s35, 0
	s_add_u32 s26, s26, 0x100
	s_addc_u32 s27, s27, 0
	s_cmp_lt_u32 s65, 14

.LBB10_19:
	s_ashr_i32 s17, s16, 31
	v_cmp_lt_i64_e32 vcc, s[0:1], v[142:143]
	s_lshl_b64 s[0:1], s[16:17], 19
	s_add_u32 s18, s33, s0
	s_addc_u32 s19, s34, s1
	s_and_b64 s[0:1], vcc, exec
	s_cselect_b32 s17, s19, s27
	s_cselect_b32 s53, s18, s26
	s_ashr_i32 s15, s14, 31
	s_lshl_b64 s[0:1], s[14:15], 19
	s_add_u32 s20, s4, s0
	s_addc_u32 s21, s5, s1
	s_and_b64 s[0:1], vcc, exec
	s_cselect_b32 s15, s21, s25
	s_cselect_b32 s54, s20, s24
	s_add_u32 s55, s24, 0x100
	s_addc_u32 s56, s25, 0
	s_add_u32 s24, s26, 0x40080
	s_addc_u32 s25, s27, 0
	s_mov_b32 s57, -2
	ds_read_b128 v[152:155], v149
	ds_read_b128 v[156:159], v149 offset:1024
	ds_read_b128 v[160:163], v149 offset:2048
	ds_read_b128 v[164:167], v149 offset:3072
	ds_read_b128 v[168:171], v150
	ds_read_b128 v[172:175], v150 offset:1024
	ds_read_b128 v[176:179], v150 offset:2048
	ds_read_b128 v[180:183], v150 offset:3072
	s_add_u32 s26, s24, 0xfffc0080
	s_addc_u32 s27, s25, -1
	s_cmp_eq_u32 s57, 12
	s_cselect_b32 s29, s17, s27
	s_cselect_b32 s28, s53, s26
	s_cselect_b32 s27, s15, s56
	s_cselect_b32 s26, s54, s55
	v_lshl_add_u64 v[146:147], s[24:25], 0, v[140:141]
	s_add_i32 m0, s35, 0xc000
	ds_read_b128 v[184:187], v151
	ds_read_b128 v[188:191], v151 offset:1024
	ds_read_b128 v[192:195], v151 offset:2048
	ds_read_b128 v[196:199], v151 offset:3072
	ds_read_b128 v[200:203], v151 offset:4096
	ds_read_b128 v[204:207], v151 offset:5120
	ds_read_b128 v[208:211], v151 offset:6144
	ds_read_b128 v[212:215], v151 offset:7168
	global_load_lds_dwordx4 v[146:147], off
	v_lshl_add_u64 v[146:147], s[24:25], 0, v[138:139]
	s_add_i32 m0, s35, 0xe000
	s_nop 0
	global_load_lds_dwordx4 v[146:147], off
	s_waitcnt vmcnt(8)
	s_waitcnt lgkmcnt(0)
	s_barrier
	s_setprio 1
	s_waitcnt lgkmcnt(0)
	v_mfma_f32_16x16x32_bf16 v[124:127], v[152:155], v[184:187], 0
	v_mfma_f32_16x16x32_bf16 v[120:123], v[160:163], v[184:187], 0
	v_mfma_f32_16x16x32_bf16 v[116:119], v[152:155], v[192:195], 0
	v_mfma_f32_16x16x32_bf16 v[108:111], v[160:163], v[192:195], 0
	v_mfma_f32_16x16x32_bf16 v[100:103], v[152:155], v[200:203], 0
	v_mfma_f32_16x16x32_bf16 v[92:95], v[160:163], v[200:203], 0
	v_mfma_f32_16x16x32_bf16 v[84:87], v[152:155], v[208:211], 0
	v_mfma_f32_16x16x32_bf16 v[76:79], v[160:163], v[208:211], 0
	v_mfma_f32_16x16x32_bf16 v[124:127], v[156:159], v[188:191], v[124:127]
	v_mfma_f32_16x16x32_bf16 v[120:123], v[164:167], v[188:191], v[120:123]
	v_mfma_f32_16x16x32_bf16 v[116:119], v[156:159], v[196:199], v[116:119]
	v_mfma_f32_16x16x32_bf16 v[108:111], v[164:167], v[196:199], v[108:111]
	v_mfma_f32_16x16x32_bf16 v[100:103], v[156:159], v[204:207], v[100:103]
	v_mfma_f32_16x16x32_bf16 v[92:95], v[164:167], v[204:207], v[92:95]
	v_mfma_f32_16x16x32_bf16 v[84:87], v[156:159], v[212:215], v[84:87]
	v_mfma_f32_16x16x32_bf16 v[76:79], v[164:167], v[212:215], v[76:79]
	s_setprio 0
	s_setprio 1
	v_mfma_f32_16x16x32_bf16 v[112:115], v[168:171], v[184:187], 0
	v_mfma_f32_16x16x32_bf16 v[104:107], v[176:179], v[184:187], 0
	v_mfma_f32_16x16x32_bf16 v[96:99], v[168:171], v[192:195], 0
	v_mfma_f32_16x16x32_bf16 v[88:91], v[176:179], v[192:195], 0
	v_mfma_f32_16x16x32_bf16 v[80:83], v[168:171], v[200:203], 0
	v_mfma_f32_16x16x32_bf16 v[72:75], v[176:179], v[200:203], 0
	v_mfma_f32_16x16x32_bf16 v[68:71], v[168:171], v[208:211], 0
	v_mfma_f32_16x16x32_bf16 v[64:67], v[176:179], v[208:211], 0
	v_mfma_f32_16x16x32_bf16 v[112:115], v[172:175], v[188:191], v[112:115]
	v_mfma_f32_16x16x32_bf16 v[104:107], v[180:183], v[188:191], v[104:107]
	v_mfma_f32_16x16x32_bf16 v[96:99], v[172:175], v[196:199], v[96:99]
	v_mfma_f32_16x16x32_bf16 v[88:91], v[180:183], v[196:199], v[88:91]
	v_mfma_f32_16x16x32_bf16 v[80:83], v[172:175], v[204:207], v[80:83]
	v_mfma_f32_16x16x32_bf16 v[72:75], v[180:183], v[204:207], v[72:75]
	v_mfma_f32_16x16x32_bf16 v[68:71], v[172:175], v[212:215], v[68:71]
	v_mfma_f32_16x16x32_bf16 v[64:67], v[180:183], v[212:215], v[64:67]
	s_setprio 0
	s_barrier
	s_add_i32 s58, s46, s31
	v_lshl_add_u64 v[146:147], s[26:27], 0, v[130:131]
	s_mov_b32 m0, s58
	ds_read_b128 v[184:187], v151 offset:16384
	ds_read_b128 v[188:191], v151 offset:17408
	ds_read_b128 v[192:195], v151 offset:18432
	ds_read_b128 v[196:199], v151 offset:19456
	ds_read_b128 v[200:203], v151 offset:20480
	ds_read_b128 v[204:207], v151 offset:21504
	ds_read_b128 v[208:211], v151 offset:22528
	ds_read_b128 v[212:215], v151 offset:23552
	global_load_lds_dwordx4 v[146:147], off
	s_add_i32 m0, s58, 0x2000
	s_add_u32 s58, s26, 0x40000
	v_lshl_add_u64 v[216:217], s[26:27], 0, v[134:135]
	s_addc_u32 s59, s27, 0
	s_add_i32 s60, s47, s31
	global_load_lds_dwordx4 v[216:217], off
	v_lshl_add_u64 v[218:219], s[58:59], 0, v[130:131]
	s_mov_b32 m0, s60
	v_lshl_add_u64 v[220:221], s[28:29], 0, v[132:133]
	global_load_lds_dwordx4 v[218:219], off
	v_lshl_add_u64 v[218:219], s[58:59], 0, v[134:135]
	s_add_i32 m0, s60, 0x2000
	s_nop 0
	global_load_lds_dwordx4 v[218:219], off
	v_lshl_add_u64 v[218:219], s[28:29], 0, v[128:129]
	s_mov_b32 m0, s35
	s_nop 0
	global_load_lds_dwordx4 v[218:219], off
	s_mov_b32 m0, s36
	s_nop 0
	global_load_lds_dwordx4 v[220:221], off
	s_waitcnt vmcnt(8)
	s_waitcnt lgkmcnt(0)
	s_barrier
	s_setprio 1
	s_waitcnt lgkmcnt(0)
	v_mfma_f32_16x16x32_bf16 v[60:63], v[152:155], v[184:187], 0
	v_mfma_f32_16x16x32_bf16 v[56:59], v[160:163], v[184:187], 0
	v_mfma_f32_16x16x32_bf16 v[52:55], v[152:155], v[192:195], 0
	v_mfma_f32_16x16x32_bf16 v[44:47], v[160:163], v[192:195], 0
	v_mfma_f32_16x16x32_bf16 v[36:39], v[152:155], v[200:203], 0
	v_mfma_f32_16x16x32_bf16 v[28:31], v[160:163], v[200:203], 0
	v_mfma_f32_16x16x32_bf16 v[20:23], v[152:155], v[208:211], 0
	v_mfma_f32_16x16x32_bf16 v[12:15], v[160:163], v[208:211], 0
	v_mfma_f32_16x16x32_bf16 v[60:63], v[156:159], v[188:191], v[60:63]
	v_mfma_f32_16x16x32_bf16 v[56:59], v[164:167], v[188:191], v[56:59]
	v_mfma_f32_16x16x32_bf16 v[52:55], v[156:159], v[196:199], v[52:55]
	v_mfma_f32_16x16x32_bf16 v[44:47], v[164:167], v[196:199], v[44:47]
	v_mfma_f32_16x16x32_bf16 v[36:39], v[156:159], v[204:207], v[36:39]
	v_mfma_f32_16x16x32_bf16 v[28:31], v[164:167], v[204:207], v[28:31]
	v_mfma_f32_16x16x32_bf16 v[20:23], v[156:159], v[212:215], v[20:23]
	v_mfma_f32_16x16x32_bf16 v[12:15], v[164:167], v[212:215], v[12:15]
	s_setprio 0
	s_setprio 1
	v_mfma_f32_16x16x32_bf16 v[48:51], v[168:171], v[184:187], 0
	v_mfma_f32_16x16x32_bf16 v[40:43], v[176:179], v[184:187], 0
	v_mfma_f32_16x16x32_bf16 v[32:35], v[168:171], v[192:195], 0
	v_mfma_f32_16x16x32_bf16 v[24:27], v[176:179], v[192:195], 0
	v_mfma_f32_16x16x32_bf16 v[16:19], v[168:171], v[200:203], 0
	v_mfma_f32_16x16x32_bf16 v[8:11], v[176:179], v[200:203], 0
	v_mfma_f32_16x16x32_bf16 v[4:7], v[168:171], v[208:211], 0
	v_mfma_f32_16x16x32_bf16 v[0:3], v[176:179], v[208:211], 0
	v_mfma_f32_16x16x32_bf16 v[48:51], v[172:175], v[188:191], v[48:51]
	v_mfma_f32_16x16x32_bf16 v[40:43], v[180:183], v[188:191], v[40:43]
	v_mfma_f32_16x16x32_bf16 v[32:35], v[172:175], v[196:199], v[32:35]
	v_mfma_f32_16x16x32_bf16 v[24:27], v[180:183], v[196:199], v[24:27]
	v_mfma_f32_16x16x32_bf16 v[16:19], v[172:175], v[204:207], v[16:19]
	v_mfma_f32_16x16x32_bf16 v[8:11], v[180:183], v[204:207], v[8:11]
	v_mfma_f32_16x16x32_bf16 v[4:7], v[172:175], v[212:215], v[4:7]
	v_mfma_f32_16x16x32_bf16 v[0:3], v[180:183], v[212:215], v[0:3]
	s_setprio 0
	s_barrier
	s_add_i32 s58, 0, 0x18000
	s_add_i32 s59, 0, 0x1c000
	v_add_u32_e32 v164, s58, v148
	v_add_u32_e32 v180, s59, v148
	ds_read_b128 v[152:155], v164
	ds_read_b128 v[156:159], v164 offset:1024
	ds_read_b128 v[160:163], v164 offset:2048
	ds_read_b128 v[164:167], v164 offset:3072
	ds_read_b128 v[168:171], v180
	ds_read_b128 v[172:175], v180 offset:1024
	ds_read_b128 v[176:179], v180 offset:2048
	ds_read_b128 v[180:183], v180 offset:3072
	s_add_u32 s28, s28, 0x40000
	s_addc_u32 s29, s29, 0
	s_mov_b32 m0, s37
	v_lshl_add_u64 v[222:223], s[28:29], 0, v[128:129]
	ds_read_b128 v[184:187], v151 offset:32768
	ds_read_b128 v[188:191], v151 offset:33792
	ds_read_b128 v[192:195], v151 offset:34816
	ds_read_b128 v[196:199], v151 offset:35840
	ds_read_b128 v[200:203], v151 offset:36864
	ds_read_b128 v[204:207], v151 offset:37888
	ds_read_b128 v[208:211], v151 offset:38912
	ds_read_b128 v[212:215], v151 offset:39936
	global_load_lds_dwordx4 v[222:223], off
	v_lshl_add_u64 v[222:223], s[28:29], 0, v[132:133]
	s_mov_b32 m0, s38
	s_nop 0
	global_load_lds_dwordx4 v[222:223], off
	s_waitcnt vmcnt(8)
	s_waitcnt lgkmcnt(0)
	s_barrier
	s_setprio 1
	s_waitcnt lgkmcnt(0)
	v_mfma_f32_16x16x32_bf16 v[124:127], v[152:155], v[184:187], v[124:127]
	v_mfma_f32_16x16x32_bf16 v[120:123], v[160:163], v[184:187], v[120:123]
	v_mfma_f32_16x16x32_bf16 v[116:119], v[152:155], v[192:195], v[116:119]
	v_mfma_f32_16x16x32_bf16 v[108:111], v[160:163], v[192:195], v[108:111]
	v_mfma_f32_16x16x32_bf16 v[100:103], v[152:155], v[200:203], v[100:103]
	v_mfma_f32_16x16x32_bf16 v[92:95], v[160:163], v[200:203], v[92:95]
	v_mfma_f32_16x16x32_bf16 v[84:87], v[152:155], v[208:211], v[84:87]
	v_mfma_f32_16x16x32_bf16 v[76:79], v[160:163], v[208:211], v[76:79]
	v_mfma_f32_16x16x32_bf16 v[124:127], v[156:159], v[188:191], v[124:127]
	v_mfma_f32_16x16x32_bf16 v[120:123], v[164:167], v[188:191], v[120:123]
	v_mfma_f32_16x16x32_bf16 v[116:119], v[156:159], v[196:199], v[116:119]
	v_mfma_f32_16x16x32_bf16 v[108:111], v[164:167], v[196:199], v[108:111]
	v_mfma_f32_16x16x32_bf16 v[100:103], v[156:159], v[204:207], v[100:103]
	v_mfma_f32_16x16x32_bf16 v[92:95], v[164:167], v[204:207], v[92:95]
	v_mfma_f32_16x16x32_bf16 v[84:87], v[156:159], v[212:215], v[84:87]
	v_mfma_f32_16x16x32_bf16 v[76:79], v[164:167], v[212:215], v[76:79]
	s_setprio 0
	s_setprio 1
	v_mfma_f32_16x16x32_bf16 v[112:115], v[168:171], v[184:187], v[112:115]
	v_mfma_f32_16x16x32_bf16 v[104:107], v[176:179], v[184:187], v[104:107]
	v_mfma_f32_16x16x32_bf16 v[96:99], v[168:171], v[192:195], v[96:99]
	v_mfma_f32_16x16x32_bf16 v[88:91], v[176:179], v[192:195], v[88:91]
	v_mfma_f32_16x16x32_bf16 v[80:83], v[168:171], v[200:203], v[80:83]
	v_mfma_f32_16x16x32_bf16 v[72:75], v[176:179], v[200:203], v[72:75]
	v_mfma_f32_16x16x32_bf16 v[68:71], v[168:171], v[208:211], v[68:71]
	v_mfma_f32_16x16x32_bf16 v[64:67], v[176:179], v[208:211], v[64:67]
	v_mfma_f32_16x16x32_bf16 v[112:115], v[172:175], v[188:191], v[112:115]
	v_mfma_f32_16x16x32_bf16 v[104:107], v[180:183], v[188:191], v[104:107]
	v_mfma_f32_16x16x32_bf16 v[96:99], v[172:175], v[196:199], v[96:99]
	v_mfma_f32_16x16x32_bf16 v[88:91], v[180:183], v[196:199], v[88:91]
	v_mfma_f32_16x16x32_bf16 v[80:83], v[172:175], v[204:207], v[80:83]
	v_mfma_f32_16x16x32_bf16 v[72:75], v[180:183], v[204:207], v[72:75]
	v_mfma_f32_16x16x32_bf16 v[68:71], v[172:175], v[212:215], v[68:71]
	v_mfma_f32_16x16x32_bf16 v[64:67], v[180:183], v[212:215], v[64:67]
	s_setprio 0
	s_barrier
	s_add_i32 s28, s58, s31
	v_lshl_add_u64 v[146:147], v[146:147], 0, s[10:11]
	s_mov_b32 m0, s28
	ds_read_b128 v[184:187], v151 offset:49152
	ds_read_b128 v[188:191], v151 offset:50176
	ds_read_b128 v[192:195], v151 offset:51200
	ds_read_b128 v[196:199], v151 offset:52224
	ds_read_b128 v[200:203], v151 offset:53248
	ds_read_b128 v[204:207], v151 offset:54272
	ds_read_b128 v[208:211], v151 offset:55296
	ds_read_b128 v[212:215], v151 offset:56320
	global_load_lds_dwordx4 v[146:147], off
	s_add_i32 m0, s28, 0x2000
	s_add_u32 s26, s26, 0x40080
	v_lshl_add_u64 v[146:147], v[216:217], 0, s[10:11]
	s_addc_u32 s27, s27, 0
	s_add_i32 s28, s59, s31
	global_load_lds_dwordx4 v[146:147], off
	v_lshl_add_u64 v[146:147], s[26:27], 0, v[130:131]
	s_mov_b32 m0, s28
	s_nop 0
	global_load_lds_dwordx4 v[146:147], off
	v_lshl_add_u64 v[146:147], s[26:27], 0, v[134:135]
	s_add_i32 m0, s28, 0x2000
	s_nop 0
	global_load_lds_dwordx4 v[146:147], off
	v_lshl_add_u64 v[146:147], v[218:219], 0, s[10:11]
	s_mov_b32 m0, s41
	s_nop 0
	global_load_lds_dwordx4 v[146:147], off
	v_lshl_add_u64 v[146:147], v[220:221], 0, s[10:11]
	s_mov_b32 m0, s42
	s_nop 0
	global_load_lds_dwordx4 v[146:147], off
	s_waitcnt vmcnt(8)
	s_waitcnt lgkmcnt(0)
	s_barrier
	s_setprio 1
	s_waitcnt lgkmcnt(0)
	v_mfma_f32_16x16x32_bf16 v[60:63], v[152:155], v[184:187], v[60:63]
	v_mfma_f32_16x16x32_bf16 v[56:59], v[160:163], v[184:187], v[56:59]
	v_mfma_f32_16x16x32_bf16 v[52:55], v[152:155], v[192:195], v[52:55]
	v_mfma_f32_16x16x32_bf16 v[44:47], v[160:163], v[192:195], v[44:47]
	v_mfma_f32_16x16x32_bf16 v[36:39], v[152:155], v[200:203], v[36:39]
	v_mfma_f32_16x16x32_bf16 v[28:31], v[160:163], v[200:203], v[28:31]
	v_mfma_f32_16x16x32_bf16 v[20:23], v[152:155], v[208:211], v[20:23]
	v_mfma_f32_16x16x32_bf16 v[12:15], v[160:163], v[208:211], v[12:15]
	v_mfma_f32_16x16x32_bf16 v[60:63], v[156:159], v[188:191], v[60:63]
	v_mfma_f32_16x16x32_bf16 v[56:59], v[164:167], v[188:191], v[56:59]
	v_mfma_f32_16x16x32_bf16 v[52:55], v[156:159], v[196:199], v[52:55]
	v_mfma_f32_16x16x32_bf16 v[44:47], v[164:167], v[196:199], v[44:47]
	v_mfma_f32_16x16x32_bf16 v[36:39], v[156:159], v[204:207], v[36:39]
	v_mfma_f32_16x16x32_bf16 v[28:31], v[164:167], v[204:207], v[28:31]
	v_mfma_f32_16x16x32_bf16 v[20:23], v[156:159], v[212:215], v[20:23]
	v_mfma_f32_16x16x32_bf16 v[12:15], v[164:167], v[212:215], v[12:15]
	s_setprio 0
	s_setprio 1
	v_mfma_f32_16x16x32_bf16 v[48:51], v[168:171], v[184:187], v[48:51]
	v_mfma_f32_16x16x32_bf16 v[40:43], v[176:179], v[184:187], v[40:43]
	v_mfma_f32_16x16x32_bf16 v[32:35], v[168:171], v[192:195], v[32:35]
	v_mfma_f32_16x16x32_bf16 v[24:27], v[176:179], v[192:195], v[24:27]
	v_mfma_f32_16x16x32_bf16 v[16:19], v[168:171], v[200:203], v[16:19]
	v_mfma_f32_16x16x32_bf16 v[8:11], v[176:179], v[200:203], v[8:11]
	v_mfma_f32_16x16x32_bf16 v[4:7], v[168:171], v[208:211], v[4:7]
	v_mfma_f32_16x16x32_bf16 v[0:3], v[176:179], v[208:211], v[0:3]
	v_mfma_f32_16x16x32_bf16 v[48:51], v[172:175], v[188:191], v[48:51]
	v_mfma_f32_16x16x32_bf16 v[40:43], v[180:183], v[188:191], v[40:43]
	v_mfma_f32_16x16x32_bf16 v[32:35], v[172:175], v[196:199], v[32:35]
	v_mfma_f32_16x16x32_bf16 v[24:27], v[180:183], v[196:199], v[24:27]
	v_mfma_f32_16x16x32_bf16 v[16:19], v[172:175], v[204:207], v[16:19]
	v_mfma_f32_16x16x32_bf16 v[8:11], v[180:183], v[204:207], v[8:11]
	v_mfma_f32_16x16x32_bf16 v[4:7], v[172:175], v[212:215], v[4:7]
	v_mfma_f32_16x16x32_bf16 v[0:3], v[180:183], v[212:215], v[0:3]
	s_setprio 0
	s_barrier
	s_add_i32 s57, s57, 2
	s_add_u32 s55, s55, 0x100
	s_addc_u32 s56, s56, 0
	s_add_u32 s24, s24, 0x100
	s_addc_u32 s25, s25, 0
	s_cmp_lt_u32 s57, 14

.LBB12_8:
	s_ashr_i32 s15, s14, 31
	v_cmp_lt_i64_e32 vcc, s[0:1], v[142:143]
	s_lshl_b64 s[0:1], s[14:15], 19
	s_add_u32 s16, s28, s0
	s_addc_u32 s17, s29, s1
	s_and_b64 s[0:1], vcc, exec
	s_cselect_b32 s15, s17, s25
	s_cselect_b32 s54, s16, s24
	s_ashr_i32 s13, s12, 31
	s_lshl_b64 s[0:1], s[12:13], 19
	s_add_u32 s18, s30, s0
	s_addc_u32 s19, s31, s1
	s_and_b64 s[0:1], vcc, exec
	s_cselect_b32 s13, s19, s23
	s_cselect_b32 s55, s18, s22
	s_add_u32 s56, s22, 0x100
	s_addc_u32 s57, s23, 0
	s_add_u32 s22, s24, 0x40080
	s_addc_u32 s23, s25, 0
	s_mov_b32 s58, -2
	ds_read_b128 v[152:155], v149
	ds_read_b128 v[156:159], v149 offset:1024
	ds_read_b128 v[160:163], v149 offset:2048
	ds_read_b128 v[164:167], v149 offset:3072
	ds_read_b128 v[168:171], v150
	ds_read_b128 v[172:175], v150 offset:1024
	ds_read_b128 v[176:179], v150 offset:2048
	ds_read_b128 v[180:183], v150 offset:3072
	s_add_u32 s24, s22, 0xfffc0080
	s_addc_u32 s25, s23, -1
	s_cmp_eq_u32 s58, 12
	s_cselect_b32 s27, s15, s25
	s_cselect_b32 s26, s54, s24
	s_cselect_b32 s25, s13, s57
	s_cselect_b32 s24, s55, s56
	v_lshl_add_u64 v[146:147], s[22:23], 0, v[140:141]
	s_add_i32 m0, s36, 0xc000
	ds_read_b128 v[184:187], v151
	ds_read_b128 v[188:191], v151 offset:1024
	ds_read_b128 v[192:195], v151 offset:2048
	ds_read_b128 v[196:199], v151 offset:3072
	ds_read_b128 v[200:203], v151 offset:4096
	ds_read_b128 v[204:207], v151 offset:5120
	ds_read_b128 v[208:211], v151 offset:6144
	ds_read_b128 v[212:215], v151 offset:7168
	global_load_lds_dwordx4 v[146:147], off
	v_lshl_add_u64 v[146:147], s[22:23], 0, v[138:139]
	s_add_i32 m0, s36, 0xe000
	s_nop 0
	global_load_lds_dwordx4 v[146:147], off
	s_waitcnt vmcnt(8)
	s_waitcnt lgkmcnt(0)
	s_barrier
	s_setprio 1
	s_waitcnt lgkmcnt(0)
	v_mfma_f32_16x16x32_bf16 v[124:127], v[152:155], v[184:187], 0
	v_mfma_f32_16x16x32_bf16 v[120:123], v[160:163], v[184:187], 0
	v_mfma_f32_16x16x32_bf16 v[108:111], v[152:155], v[192:195], 0
	v_mfma_f32_16x16x32_bf16 v[104:107], v[160:163], v[192:195], 0
	v_mfma_f32_16x16x32_bf16 v[92:95], v[152:155], v[200:203], 0
	v_mfma_f32_16x16x32_bf16 v[88:91], v[160:163], v[200:203], 0
	v_mfma_f32_16x16x32_bf16 v[76:79], v[152:155], v[208:211], 0
	v_mfma_f32_16x16x32_bf16 v[72:75], v[160:163], v[208:211], 0
	v_mfma_f32_16x16x32_bf16 v[124:127], v[156:159], v[188:191], v[124:127]
	v_mfma_f32_16x16x32_bf16 v[120:123], v[164:167], v[188:191], v[120:123]
	v_mfma_f32_16x16x32_bf16 v[108:111], v[156:159], v[196:199], v[108:111]
	v_mfma_f32_16x16x32_bf16 v[104:107], v[164:167], v[196:199], v[104:107]
	v_mfma_f32_16x16x32_bf16 v[92:95], v[156:159], v[204:207], v[92:95]
	v_mfma_f32_16x16x32_bf16 v[88:91], v[164:167], v[204:207], v[88:91]
	v_mfma_f32_16x16x32_bf16 v[76:79], v[156:159], v[212:215], v[76:79]
	v_mfma_f32_16x16x32_bf16 v[72:75], v[164:167], v[212:215], v[72:75]
	s_setprio 0
	s_setprio 1
	v_mfma_f32_16x16x32_bf16 v[116:119], v[168:171], v[184:187], 0
	v_mfma_f32_16x16x32_bf16 v[112:115], v[176:179], v[184:187], 0
	v_mfma_f32_16x16x32_bf16 v[100:103], v[168:171], v[192:195], 0
	v_mfma_f32_16x16x32_bf16 v[96:99], v[176:179], v[192:195], 0
	v_mfma_f32_16x16x32_bf16 v[84:87], v[168:171], v[200:203], 0
	v_mfma_f32_16x16x32_bf16 v[80:83], v[176:179], v[200:203], 0
	v_mfma_f32_16x16x32_bf16 v[68:71], v[168:171], v[208:211], 0
	v_mfma_f32_16x16x32_bf16 v[64:67], v[176:179], v[208:211], 0
	v_mfma_f32_16x16x32_bf16 v[116:119], v[172:175], v[188:191], v[116:119]
	v_mfma_f32_16x16x32_bf16 v[112:115], v[180:183], v[188:191], v[112:115]
	v_mfma_f32_16x16x32_bf16 v[100:103], v[172:175], v[196:199], v[100:103]
	v_mfma_f32_16x16x32_bf16 v[96:99], v[180:183], v[196:199], v[96:99]
	v_mfma_f32_16x16x32_bf16 v[84:87], v[172:175], v[204:207], v[84:87]
	v_mfma_f32_16x16x32_bf16 v[80:83], v[180:183], v[204:207], v[80:83]
	v_mfma_f32_16x16x32_bf16 v[68:71], v[172:175], v[212:215], v[68:71]
	v_mfma_f32_16x16x32_bf16 v[64:67], v[180:183], v[212:215], v[64:67]
	s_setprio 0
	s_barrier
	s_add_i32 s59, s44, s33
	v_lshl_add_u64 v[146:147], s[24:25], 0, v[132:133]
	s_mov_b32 m0, s59
	ds_read_b128 v[184:187], v151 offset:16384
	ds_read_b128 v[188:191], v151 offset:17408
	ds_read_b128 v[192:195], v151 offset:18432
	ds_read_b128 v[196:199], v151 offset:19456
	ds_read_b128 v[200:203], v151 offset:20480
	ds_read_b128 v[204:207], v151 offset:21504
	ds_read_b128 v[208:211], v151 offset:22528
	ds_read_b128 v[212:215], v151 offset:23552
	global_load_lds_dwordx4 v[146:147], off
	s_add_i32 m0, s59, 0x2000
	s_add_u32 s60, s24, 0x40000
	v_lshl_add_u64 v[216:217], s[24:25], 0, v[128:129]
	s_addc_u32 s61, s25, 0
	s_add_i32 s59, s45, s33
	global_load_lds_dwordx4 v[216:217], off
	v_lshl_add_u64 v[218:219], s[60:61], 0, v[132:133]
	s_mov_b32 m0, s59
	v_lshl_add_u64 v[220:221], s[26:27], 0, v[130:131]
	global_load_lds_dwordx4 v[218:219], off
	v_lshl_add_u64 v[218:219], s[60:61], 0, v[128:129]
	s_add_i32 m0, s59, 0x2000
	s_nop 0
	global_load_lds_dwordx4 v[218:219], off
	v_lshl_add_u64 v[218:219], s[26:27], 0, v[134:135]
	s_mov_b32 m0, s36
	s_nop 0
	global_load_lds_dwordx4 v[218:219], off
	s_mov_b32 m0, s37
	s_nop 0
	global_load_lds_dwordx4 v[220:221], off
	s_waitcnt vmcnt(8)
	s_waitcnt lgkmcnt(0)
	s_barrier
	s_setprio 1
	s_waitcnt lgkmcnt(0)
	v_mfma_f32_16x16x32_bf16 v[60:63], v[152:155], v[184:187], 0
	v_mfma_f32_16x16x32_bf16 v[56:59], v[160:163], v[184:187], 0
	v_mfma_f32_16x16x32_bf16 v[44:47], v[152:155], v[192:195], 0
	v_mfma_f32_16x16x32_bf16 v[40:43], v[160:163], v[192:195], 0
	v_mfma_f32_16x16x32_bf16 v[28:31], v[152:155], v[200:203], 0
	v_mfma_f32_16x16x32_bf16 v[24:27], v[160:163], v[200:203], 0
	v_mfma_f32_16x16x32_bf16 v[12:15], v[152:155], v[208:211], 0
	v_mfma_f32_16x16x32_bf16 v[8:11], v[160:163], v[208:211], 0
	v_mfma_f32_16x16x32_bf16 v[60:63], v[156:159], v[188:191], v[60:63]
	v_mfma_f32_16x16x32_bf16 v[56:59], v[164:167], v[188:191], v[56:59]
	v_mfma_f32_16x16x32_bf16 v[44:47], v[156:159], v[196:199], v[44:47]
	v_mfma_f32_16x16x32_bf16 v[40:43], v[164:167], v[196:199], v[40:43]
	v_mfma_f32_16x16x32_bf16 v[28:31], v[156:159], v[204:207], v[28:31]
	v_mfma_f32_16x16x32_bf16 v[24:27], v[164:167], v[204:207], v[24:27]
	v_mfma_f32_16x16x32_bf16 v[12:15], v[156:159], v[212:215], v[12:15]
	v_mfma_f32_16x16x32_bf16 v[8:11], v[164:167], v[212:215], v[8:11]
	s_setprio 0
	s_setprio 1
	v_mfma_f32_16x16x32_bf16 v[52:55], v[168:171], v[184:187], 0
	v_mfma_f32_16x16x32_bf16 v[48:51], v[176:179], v[184:187], 0
	v_mfma_f32_16x16x32_bf16 v[36:39], v[168:171], v[192:195], 0
	v_mfma_f32_16x16x32_bf16 v[32:35], v[176:179], v[192:195], 0
	v_mfma_f32_16x16x32_bf16 v[20:23], v[168:171], v[200:203], 0
	v_mfma_f32_16x16x32_bf16 v[16:19], v[176:179], v[200:203], 0
	v_mfma_f32_16x16x32_bf16 v[4:7], v[168:171], v[208:211], 0
	v_mfma_f32_16x16x32_bf16 v[0:3], v[176:179], v[208:211], 0
	v_mfma_f32_16x16x32_bf16 v[52:55], v[172:175], v[188:191], v[52:55]
	v_mfma_f32_16x16x32_bf16 v[48:51], v[180:183], v[188:191], v[48:51]
	v_mfma_f32_16x16x32_bf16 v[36:39], v[172:175], v[196:199], v[36:39]
	v_mfma_f32_16x16x32_bf16 v[32:35], v[180:183], v[196:199], v[32:35]
	v_mfma_f32_16x16x32_bf16 v[20:23], v[172:175], v[204:207], v[20:23]
	v_mfma_f32_16x16x32_bf16 v[16:19], v[180:183], v[204:207], v[16:19]
	v_mfma_f32_16x16x32_bf16 v[4:7], v[172:175], v[212:215], v[4:7]
	v_mfma_f32_16x16x32_bf16 v[0:3], v[180:183], v[212:215], v[0:3]
	s_setprio 0
	s_barrier
	s_add_i32 s59, 0, 0x18000
	s_add_i32 s60, 0, 0x1c000
	v_add_u32_e32 v164, s59, v148
	v_add_u32_e32 v180, s60, v148
	ds_read_b128 v[152:155], v164
	ds_read_b128 v[156:159], v164 offset:1024
	ds_read_b128 v[160:163], v164 offset:2048
	ds_read_b128 v[164:167], v164 offset:3072
	ds_read_b128 v[168:171], v180
	ds_read_b128 v[172:175], v180 offset:1024
	ds_read_b128 v[176:179], v180 offset:2048
	ds_read_b128 v[180:183], v180 offset:3072
	s_add_u32 s26, s26, 0x40000
	s_addc_u32 s27, s27, 0
	s_mov_b32 m0, s38
	v_lshl_add_u64 v[222:223], s[26:27], 0, v[134:135]
	ds_read_b128 v[184:187], v151 offset:32768
	ds_read_b128 v[188:191], v151 offset:33792
	ds_read_b128 v[192:195], v151 offset:34816
	ds_read_b128 v[196:199], v151 offset:35840
	ds_read_b128 v[200:203], v151 offset:36864
	ds_read_b128 v[204:207], v151 offset:37888
	ds_read_b128 v[208:211], v151 offset:38912
	ds_read_b128 v[212:215], v151 offset:39936
	global_load_lds_dwordx4 v[222:223], off
	v_lshl_add_u64 v[222:223], s[26:27], 0, v[130:131]
	s_mov_b32 m0, s39
	s_nop 0
	global_load_lds_dwordx4 v[222:223], off
	s_waitcnt vmcnt(8)
	s_waitcnt lgkmcnt(0)
	s_barrier
	s_setprio 1
	s_waitcnt lgkmcnt(0)
	v_mfma_f32_16x16x32_bf16 v[124:127], v[152:155], v[184:187], v[124:127]
	v_mfma_f32_16x16x32_bf16 v[120:123], v[160:163], v[184:187], v[120:123]
	v_mfma_f32_16x16x32_bf16 v[108:111], v[152:155], v[192:195], v[108:111]
	v_mfma_f32_16x16x32_bf16 v[104:107], v[160:163], v[192:195], v[104:107]
	v_mfma_f32_16x16x32_bf16 v[92:95], v[152:155], v[200:203], v[92:95]
	v_mfma_f32_16x16x32_bf16 v[88:91], v[160:163], v[200:203], v[88:91]
	v_mfma_f32_16x16x32_bf16 v[76:79], v[152:155], v[208:211], v[76:79]
	v_mfma_f32_16x16x32_bf16 v[72:75], v[160:163], v[208:211], v[72:75]
	v_mfma_f32_16x16x32_bf16 v[124:127], v[156:159], v[188:191], v[124:127]
	v_mfma_f32_16x16x32_bf16 v[120:123], v[164:167], v[188:191], v[120:123]
	v_mfma_f32_16x16x32_bf16 v[108:111], v[156:159], v[196:199], v[108:111]
	v_mfma_f32_16x16x32_bf16 v[104:107], v[164:167], v[196:199], v[104:107]
	v_mfma_f32_16x16x32_bf16 v[92:95], v[156:159], v[204:207], v[92:95]
	v_mfma_f32_16x16x32_bf16 v[88:91], v[164:167], v[204:207], v[88:91]
	v_mfma_f32_16x16x32_bf16 v[76:79], v[156:159], v[212:215], v[76:79]
	v_mfma_f32_16x16x32_bf16 v[72:75], v[164:167], v[212:215], v[72:75]
	s_setprio 0
	s_setprio 1
	v_mfma_f32_16x16x32_bf16 v[116:119], v[168:171], v[184:187], v[116:119]
	v_mfma_f32_16x16x32_bf16 v[112:115], v[176:179], v[184:187], v[112:115]
	v_mfma_f32_16x16x32_bf16 v[100:103], v[168:171], v[192:195], v[100:103]
	v_mfma_f32_16x16x32_bf16 v[96:99], v[176:179], v[192:195], v[96:99]
	v_mfma_f32_16x16x32_bf16 v[84:87], v[168:171], v[200:203], v[84:87]
	v_mfma_f32_16x16x32_bf16 v[80:83], v[176:179], v[200:203], v[80:83]
	v_mfma_f32_16x16x32_bf16 v[68:71], v[168:171], v[208:211], v[68:71]
	v_mfma_f32_16x16x32_bf16 v[64:67], v[176:179], v[208:211], v[64:67]
	v_mfma_f32_16x16x32_bf16 v[116:119], v[172:175], v[188:191], v[116:119]
	v_mfma_f32_16x16x32_bf16 v[112:115], v[180:183], v[188:191], v[112:115]
	v_mfma_f32_16x16x32_bf16 v[100:103], v[172:175], v[196:199], v[100:103]
	v_mfma_f32_16x16x32_bf16 v[96:99], v[180:183], v[196:199], v[96:99]
	v_mfma_f32_16x16x32_bf16 v[84:87], v[172:175], v[204:207], v[84:87]
	v_mfma_f32_16x16x32_bf16 v[80:83], v[180:183], v[204:207], v[80:83]
	v_mfma_f32_16x16x32_bf16 v[68:71], v[172:175], v[212:215], v[68:71]
	v_mfma_f32_16x16x32_bf16 v[64:67], v[180:183], v[212:215], v[64:67]
	s_setprio 0
	s_barrier
	s_add_i32 s26, s59, s33
	v_lshl_add_u64 v[146:147], v[146:147], 0, s[8:9]
	s_mov_b32 m0, s26
	ds_read_b128 v[184:187], v151 offset:49152
	ds_read_b128 v[188:191], v151 offset:50176
	ds_read_b128 v[192:195], v151 offset:51200
	ds_read_b128 v[196:199], v151 offset:52224
	ds_read_b128 v[200:203], v151 offset:53248
	ds_read_b128 v[204:207], v151 offset:54272
	ds_read_b128 v[208:211], v151 offset:55296
	ds_read_b128 v[212:215], v151 offset:56320
	global_load_lds_dwordx4 v[146:147], off
	s_add_i32 m0, s26, 0x2000
	s_add_u32 s24, s24, 0x40080
	v_lshl_add_u64 v[146:147], v[216:217], 0, s[8:9]
	s_addc_u32 s25, s25, 0
	s_add_i32 s26, s60, s33
	global_load_lds_dwordx4 v[146:147], off
	v_lshl_add_u64 v[146:147], s[24:25], 0, v[132:133]
	s_mov_b32 m0, s26
	s_nop 0
	global_load_lds_dwordx4 v[146:147], off
	v_lshl_add_u64 v[146:147], s[24:25], 0, v[128:129]
	s_add_i32 m0, s26, 0x2000
	s_nop 0
	global_load_lds_dwordx4 v[146:147], off
	v_lshl_add_u64 v[146:147], v[218:219], 0, s[8:9]
	s_mov_b32 m0, s41
	s_nop 0
	global_load_lds_dwordx4 v[146:147], off
	v_lshl_add_u64 v[146:147], v[220:221], 0, s[8:9]
	s_mov_b32 m0, s42
	s_nop 0
	global_load_lds_dwordx4 v[146:147], off
	s_waitcnt vmcnt(8)
	s_waitcnt lgkmcnt(0)
	s_barrier
	s_setprio 1
	s_waitcnt lgkmcnt(0)
	v_mfma_f32_16x16x32_bf16 v[60:63], v[152:155], v[184:187], v[60:63]
	v_mfma_f32_16x16x32_bf16 v[56:59], v[160:163], v[184:187], v[56:59]
	v_mfma_f32_16x16x32_bf16 v[44:47], v[152:155], v[192:195], v[44:47]
	v_mfma_f32_16x16x32_bf16 v[40:43], v[160:163], v[192:195], v[40:43]
	v_mfma_f32_16x16x32_bf16 v[28:31], v[152:155], v[200:203], v[28:31]
	v_mfma_f32_16x16x32_bf16 v[24:27], v[160:163], v[200:203], v[24:27]
	v_mfma_f32_16x16x32_bf16 v[12:15], v[152:155], v[208:211], v[12:15]
	v_mfma_f32_16x16x32_bf16 v[8:11], v[160:163], v[208:211], v[8:11]
	v_mfma_f32_16x16x32_bf16 v[60:63], v[156:159], v[188:191], v[60:63]
	v_mfma_f32_16x16x32_bf16 v[56:59], v[164:167], v[188:191], v[56:59]
	v_mfma_f32_16x16x32_bf16 v[44:47], v[156:159], v[196:199], v[44:47]
	v_mfma_f32_16x16x32_bf16 v[40:43], v[164:167], v[196:199], v[40:43]
	v_mfma_f32_16x16x32_bf16 v[28:31], v[156:159], v[204:207], v[28:31]
	v_mfma_f32_16x16x32_bf16 v[24:27], v[164:167], v[204:207], v[24:27]
	v_mfma_f32_16x16x32_bf16 v[12:15], v[156:159], v[212:215], v[12:15]
	v_mfma_f32_16x16x32_bf16 v[8:11], v[164:167], v[212:215], v[8:11]
	s_setprio 0
	s_setprio 1
	v_mfma_f32_16x16x32_bf16 v[52:55], v[168:171], v[184:187], v[52:55]
	v_mfma_f32_16x16x32_bf16 v[48:51], v[176:179], v[184:187], v[48:51]
	v_mfma_f32_16x16x32_bf16 v[36:39], v[168:171], v[192:195], v[36:39]
	v_mfma_f32_16x16x32_bf16 v[32:35], v[176:179], v[192:195], v[32:35]
	v_mfma_f32_16x16x32_bf16 v[20:23], v[168:171], v[200:203], v[20:23]
	v_mfma_f32_16x16x32_bf16 v[16:19], v[176:179], v[200:203], v[16:19]
	v_mfma_f32_16x16x32_bf16 v[4:7], v[168:171], v[208:211], v[4:7]
	v_mfma_f32_16x16x32_bf16 v[0:3], v[176:179], v[208:211], v[0:3]
	v_mfma_f32_16x16x32_bf16 v[52:55], v[172:175], v[188:191], v[52:55]
	v_mfma_f32_16x16x32_bf16 v[48:51], v[180:183], v[188:191], v[48:51]
	v_mfma_f32_16x16x32_bf16 v[36:39], v[172:175], v[196:199], v[36:39]
	v_mfma_f32_16x16x32_bf16 v[32:35], v[180:183], v[196:199], v[32:35]
	v_mfma_f32_16x16x32_bf16 v[20:23], v[172:175], v[204:207], v[20:23]
	v_mfma_f32_16x16x32_bf16 v[16:19], v[180:183], v[204:207], v[16:19]
	v_mfma_f32_16x16x32_bf16 v[4:7], v[172:175], v[212:215], v[4:7]
	v_mfma_f32_16x16x32_bf16 v[0:3], v[180:183], v[212:215], v[0:3]
	s_setprio 0
	s_barrier
	s_add_i32 s58, s58, 2
	s_add_u32 s56, s56, 0x100
	s_addc_u32 s57, s57, 0
	s_add_u32 s22, s22, 0x100
	s_addc_u32 s23, s23, 0
	s_cmp_lt_u32 s58, 14

.LBB13_19:
	s_ashr_i32 s17, s16, 31
	v_cmp_lt_i64_e32 vcc, s[0:1], v[142:143]
	s_lshl_b64 s[0:1], s[16:17], 21
	s_add_u32 s18, s33, s0
	s_addc_u32 s19, s34, s1
	s_and_b64 s[0:1], vcc, exec
	s_cselect_b32 s17, s19, s27
	s_cselect_b32 s53, s18, s26
	s_ashr_i32 s15, s14, 31
	s_lshl_b64 s[0:1], s[14:15], 21
	s_add_u32 s20, s4, s0
	s_addc_u32 s21, s5, s1
	s_and_b64 s[0:1], vcc, exec
	s_cselect_b32 s15, s21, s25
	s_cselect_b32 s54, s20, s24
	s_add_u32 s55, s24, 0x100
	s_addc_u32 s56, s25, 0
	s_add_u32 s24, s26, 0x100080
	s_addc_u32 s25, s27, 0
	s_mov_b32 s57, -2
	ds_read_b128 v[152:155], v149
	ds_read_b128 v[156:159], v149 offset:1024
	ds_read_b128 v[160:163], v149 offset:2048
	ds_read_b128 v[164:167], v149 offset:3072
	ds_read_b128 v[168:171], v150
	ds_read_b128 v[172:175], v150 offset:1024
	ds_read_b128 v[176:179], v150 offset:2048
	ds_read_b128 v[180:183], v150 offset:3072
	s_add_u32 s26, s24, 0xfff00080
	s_addc_u32 s27, s25, -1
	s_cmp_eq_u32 s57, 60
	s_cselect_b32 s29, s17, s27
	s_cselect_b32 s28, s53, s26
	s_cselect_b32 s27, s15, s56
	s_cselect_b32 s26, s54, s55
	v_lshl_add_u64 v[146:147], s[24:25], 0, v[140:141]
	s_add_i32 m0, s35, 0xc000
	ds_read_b128 v[184:187], v151
	ds_read_b128 v[188:191], v151 offset:1024
	ds_read_b128 v[192:195], v151 offset:2048
	ds_read_b128 v[196:199], v151 offset:3072
	ds_read_b128 v[200:203], v151 offset:4096
	ds_read_b128 v[204:207], v151 offset:5120
	ds_read_b128 v[208:211], v151 offset:6144
	ds_read_b128 v[212:215], v151 offset:7168
	global_load_lds_dwordx4 v[146:147], off
	v_lshl_add_u64 v[146:147], s[24:25], 0, v[138:139]
	s_add_i32 m0, s35, 0xe000
	s_nop 0
	global_load_lds_dwordx4 v[146:147], off
	s_waitcnt vmcnt(8)
	s_waitcnt lgkmcnt(0)
	s_barrier
	s_setprio 1
	s_waitcnt lgkmcnt(0)
	v_mfma_f32_16x16x32_bf16 v[124:127], v[152:155], v[184:187], 0
	v_mfma_f32_16x16x32_bf16 v[120:123], v[160:163], v[184:187], 0
	v_mfma_f32_16x16x32_bf16 v[116:119], v[152:155], v[192:195], 0
	v_mfma_f32_16x16x32_bf16 v[108:111], v[160:163], v[192:195], 0
	v_mfma_f32_16x16x32_bf16 v[100:103], v[152:155], v[200:203], 0
	v_mfma_f32_16x16x32_bf16 v[92:95], v[160:163], v[200:203], 0
	v_mfma_f32_16x16x32_bf16 v[84:87], v[152:155], v[208:211], 0
	v_mfma_f32_16x16x32_bf16 v[76:79], v[160:163], v[208:211], 0
	v_mfma_f32_16x16x32_bf16 v[124:127], v[156:159], v[188:191], v[124:127]
	v_mfma_f32_16x16x32_bf16 v[120:123], v[164:167], v[188:191], v[120:123]
	v_mfma_f32_16x16x32_bf16 v[116:119], v[156:159], v[196:199], v[116:119]
	v_mfma_f32_16x16x32_bf16 v[108:111], v[164:167], v[196:199], v[108:111]
	v_mfma_f32_16x16x32_bf16 v[100:103], v[156:159], v[204:207], v[100:103]
	v_mfma_f32_16x16x32_bf16 v[92:95], v[164:167], v[204:207], v[92:95]
	v_mfma_f32_16x16x32_bf16 v[84:87], v[156:159], v[212:215], v[84:87]
	v_mfma_f32_16x16x32_bf16 v[76:79], v[164:167], v[212:215], v[76:79]
	s_setprio 0
	s_setprio 1
	v_mfma_f32_16x16x32_bf16 v[112:115], v[168:171], v[184:187], 0
	v_mfma_f32_16x16x32_bf16 v[104:107], v[176:179], v[184:187], 0
	v_mfma_f32_16x16x32_bf16 v[96:99], v[168:171], v[192:195], 0
	v_mfma_f32_16x16x32_bf16 v[88:91], v[176:179], v[192:195], 0
	v_mfma_f32_16x16x32_bf16 v[80:83], v[168:171], v[200:203], 0
	v_mfma_f32_16x16x32_bf16 v[72:75], v[176:179], v[200:203], 0
	v_mfma_f32_16x16x32_bf16 v[68:71], v[168:171], v[208:211], 0
	v_mfma_f32_16x16x32_bf16 v[64:67], v[176:179], v[208:211], 0
	v_mfma_f32_16x16x32_bf16 v[112:115], v[172:175], v[188:191], v[112:115]
	v_mfma_f32_16x16x32_bf16 v[104:107], v[180:183], v[188:191], v[104:107]
	v_mfma_f32_16x16x32_bf16 v[96:99], v[172:175], v[196:199], v[96:99]
	v_mfma_f32_16x16x32_bf16 v[88:91], v[180:183], v[196:199], v[88:91]
	v_mfma_f32_16x16x32_bf16 v[80:83], v[172:175], v[204:207], v[80:83]
	v_mfma_f32_16x16x32_bf16 v[72:75], v[180:183], v[204:207], v[72:75]
	v_mfma_f32_16x16x32_bf16 v[68:71], v[172:175], v[212:215], v[68:71]
	v_mfma_f32_16x16x32_bf16 v[64:67], v[180:183], v[212:215], v[64:67]
	s_setprio 0
	s_barrier
	s_add_i32 s58, s46, s31
	v_lshl_add_u64 v[146:147], s[26:27], 0, v[130:131]
	s_mov_b32 m0, s58
	ds_read_b128 v[184:187], v151 offset:16384
	ds_read_b128 v[188:191], v151 offset:17408
	ds_read_b128 v[192:195], v151 offset:18432
	ds_read_b128 v[196:199], v151 offset:19456
	ds_read_b128 v[200:203], v151 offset:20480
	ds_read_b128 v[204:207], v151 offset:21504
	ds_read_b128 v[208:211], v151 offset:22528
	ds_read_b128 v[212:215], v151 offset:23552
	global_load_lds_dwordx4 v[146:147], off
	s_add_i32 m0, s58, 0x2000
	s_add_u32 s58, s26, 0x100000
	v_lshl_add_u64 v[216:217], s[26:27], 0, v[134:135]
	s_addc_u32 s59, s27, 0
	s_add_i32 s60, s47, s31
	global_load_lds_dwordx4 v[216:217], off
	v_lshl_add_u64 v[218:219], s[58:59], 0, v[130:131]
	s_mov_b32 m0, s60
	v_lshl_add_u64 v[220:221], s[28:29], 0, v[132:133]
	global_load_lds_dwordx4 v[218:219], off
	v_lshl_add_u64 v[218:219], s[58:59], 0, v[134:135]
	s_add_i32 m0, s60, 0x2000
	s_nop 0
	global_load_lds_dwordx4 v[218:219], off
	v_lshl_add_u64 v[218:219], s[28:29], 0, v[128:129]
	s_mov_b32 m0, s35
	s_nop 0
	global_load_lds_dwordx4 v[218:219], off
	s_mov_b32 m0, s36
	s_nop 0
	global_load_lds_dwordx4 v[220:221], off
	s_waitcnt vmcnt(8)
	s_waitcnt lgkmcnt(0)
	s_barrier
	s_setprio 1
	s_waitcnt lgkmcnt(0)
	v_mfma_f32_16x16x32_bf16 v[60:63], v[152:155], v[184:187], 0
	v_mfma_f32_16x16x32_bf16 v[56:59], v[160:163], v[184:187], 0
	v_mfma_f32_16x16x32_bf16 v[52:55], v[152:155], v[192:195], 0
	v_mfma_f32_16x16x32_bf16 v[44:47], v[160:163], v[192:195], 0
	v_mfma_f32_16x16x32_bf16 v[36:39], v[152:155], v[200:203], 0
	v_mfma_f32_16x16x32_bf16 v[28:31], v[160:163], v[200:203], 0
	v_mfma_f32_16x16x32_bf16 v[20:23], v[152:155], v[208:211], 0
	v_mfma_f32_16x16x32_bf16 v[12:15], v[160:163], v[208:211], 0
	v_mfma_f32_16x16x32_bf16 v[60:63], v[156:159], v[188:191], v[60:63]
	v_mfma_f32_16x16x32_bf16 v[56:59], v[164:167], v[188:191], v[56:59]
	v_mfma_f32_16x16x32_bf16 v[52:55], v[156:159], v[196:199], v[52:55]
	v_mfma_f32_16x16x32_bf16 v[44:47], v[164:167], v[196:199], v[44:47]
	v_mfma_f32_16x16x32_bf16 v[36:39], v[156:159], v[204:207], v[36:39]
	v_mfma_f32_16x16x32_bf16 v[28:31], v[164:167], v[204:207], v[28:31]
	v_mfma_f32_16x16x32_bf16 v[20:23], v[156:159], v[212:215], v[20:23]
	v_mfma_f32_16x16x32_bf16 v[12:15], v[164:167], v[212:215], v[12:15]
	s_setprio 0
	s_setprio 1
	v_mfma_f32_16x16x32_bf16 v[48:51], v[168:171], v[184:187], 0
	v_mfma_f32_16x16x32_bf16 v[40:43], v[176:179], v[184:187], 0
	v_mfma_f32_16x16x32_bf16 v[32:35], v[168:171], v[192:195], 0
	v_mfma_f32_16x16x32_bf16 v[24:27], v[176:179], v[192:195], 0
	v_mfma_f32_16x16x32_bf16 v[16:19], v[168:171], v[200:203], 0
	v_mfma_f32_16x16x32_bf16 v[8:11], v[176:179], v[200:203], 0
	v_mfma_f32_16x16x32_bf16 v[4:7], v[168:171], v[208:211], 0
	v_mfma_f32_16x16x32_bf16 v[0:3], v[176:179], v[208:211], 0
	v_mfma_f32_16x16x32_bf16 v[48:51], v[172:175], v[188:191], v[48:51]
	v_mfma_f32_16x16x32_bf16 v[40:43], v[180:183], v[188:191], v[40:43]
	v_mfma_f32_16x16x32_bf16 v[32:35], v[172:175], v[196:199], v[32:35]
	v_mfma_f32_16x16x32_bf16 v[24:27], v[180:183], v[196:199], v[24:27]
	v_mfma_f32_16x16x32_bf16 v[16:19], v[172:175], v[204:207], v[16:19]
	v_mfma_f32_16x16x32_bf16 v[8:11], v[180:183], v[204:207], v[8:11]
	v_mfma_f32_16x16x32_bf16 v[4:7], v[172:175], v[212:215], v[4:7]
	v_mfma_f32_16x16x32_bf16 v[0:3], v[180:183], v[212:215], v[0:3]
	s_setprio 0
	s_barrier
	s_add_i32 s58, 0, 0x18000
	s_add_i32 s59, 0, 0x1c000
	v_add_u32_e32 v164, s58, v148
	v_add_u32_e32 v180, s59, v148
	ds_read_b128 v[152:155], v164
	ds_read_b128 v[156:159], v164 offset:1024
	ds_read_b128 v[160:163], v164 offset:2048
	ds_read_b128 v[164:167], v164 offset:3072
	ds_read_b128 v[168:171], v180
	ds_read_b128 v[172:175], v180 offset:1024
	ds_read_b128 v[176:179], v180 offset:2048
	ds_read_b128 v[180:183], v180 offset:3072
	s_add_u32 s28, s28, 0x100000
	s_addc_u32 s29, s29, 0
	s_mov_b32 m0, s37
	v_lshl_add_u64 v[222:223], s[28:29], 0, v[128:129]
	ds_read_b128 v[184:187], v151 offset:32768
	ds_read_b128 v[188:191], v151 offset:33792
	ds_read_b128 v[192:195], v151 offset:34816
	ds_read_b128 v[196:199], v151 offset:35840
	ds_read_b128 v[200:203], v151 offset:36864
	ds_read_b128 v[204:207], v151 offset:37888
	ds_read_b128 v[208:211], v151 offset:38912
	ds_read_b128 v[212:215], v151 offset:39936
	global_load_lds_dwordx4 v[222:223], off
	v_lshl_add_u64 v[222:223], s[28:29], 0, v[132:133]
	s_mov_b32 m0, s38
	s_nop 0
	global_load_lds_dwordx4 v[222:223], off
	s_waitcnt vmcnt(8)
	s_waitcnt lgkmcnt(0)
	s_barrier
	s_setprio 1
	s_waitcnt lgkmcnt(0)
	v_mfma_f32_16x16x32_bf16 v[124:127], v[152:155], v[184:187], v[124:127]
	v_mfma_f32_16x16x32_bf16 v[120:123], v[160:163], v[184:187], v[120:123]
	v_mfma_f32_16x16x32_bf16 v[116:119], v[152:155], v[192:195], v[116:119]
	v_mfma_f32_16x16x32_bf16 v[108:111], v[160:163], v[192:195], v[108:111]
	v_mfma_f32_16x16x32_bf16 v[100:103], v[152:155], v[200:203], v[100:103]
	v_mfma_f32_16x16x32_bf16 v[92:95], v[160:163], v[200:203], v[92:95]
	v_mfma_f32_16x16x32_bf16 v[84:87], v[152:155], v[208:211], v[84:87]
	v_mfma_f32_16x16x32_bf16 v[76:79], v[160:163], v[208:211], v[76:79]
	v_mfma_f32_16x16x32_bf16 v[124:127], v[156:159], v[188:191], v[124:127]
	v_mfma_f32_16x16x32_bf16 v[120:123], v[164:167], v[188:191], v[120:123]
	v_mfma_f32_16x16x32_bf16 v[116:119], v[156:159], v[196:199], v[116:119]
	v_mfma_f32_16x16x32_bf16 v[108:111], v[164:167], v[196:199], v[108:111]
	v_mfma_f32_16x16x32_bf16 v[100:103], v[156:159], v[204:207], v[100:103]
	v_mfma_f32_16x16x32_bf16 v[92:95], v[164:167], v[204:207], v[92:95]
	v_mfma_f32_16x16x32_bf16 v[84:87], v[156:159], v[212:215], v[84:87]
	v_mfma_f32_16x16x32_bf16 v[76:79], v[164:167], v[212:215], v[76:79]
	s_setprio 0
	s_setprio 1
	v_mfma_f32_16x16x32_bf16 v[112:115], v[168:171], v[184:187], v[112:115]
	v_mfma_f32_16x16x32_bf16 v[104:107], v[176:179], v[184:187], v[104:107]
	v_mfma_f32_16x16x32_bf16 v[96:99], v[168:171], v[192:195], v[96:99]
	v_mfma_f32_16x16x32_bf16 v[88:91], v[176:179], v[192:195], v[88:91]
	v_mfma_f32_16x16x32_bf16 v[80:83], v[168:171], v[200:203], v[80:83]
	v_mfma_f32_16x16x32_bf16 v[72:75], v[176:179], v[200:203], v[72:75]
	v_mfma_f32_16x16x32_bf16 v[68:71], v[168:171], v[208:211], v[68:71]
	v_mfma_f32_16x16x32_bf16 v[64:67], v[176:179], v[208:211], v[64:67]
	v_mfma_f32_16x16x32_bf16 v[112:115], v[172:175], v[188:191], v[112:115]
	v_mfma_f32_16x16x32_bf16 v[104:107], v[180:183], v[188:191], v[104:107]
	v_mfma_f32_16x16x32_bf16 v[96:99], v[172:175], v[196:199], v[96:99]
	v_mfma_f32_16x16x32_bf16 v[88:91], v[180:183], v[196:199], v[88:91]
	v_mfma_f32_16x16x32_bf16 v[80:83], v[172:175], v[204:207], v[80:83]
	v_mfma_f32_16x16x32_bf16 v[72:75], v[180:183], v[204:207], v[72:75]
	v_mfma_f32_16x16x32_bf16 v[68:71], v[172:175], v[212:215], v[68:71]
	v_mfma_f32_16x16x32_bf16 v[64:67], v[180:183], v[212:215], v[64:67]
	s_setprio 0
	s_barrier
	s_add_i32 s28, s58, s31
	v_lshl_add_u64 v[146:147], v[146:147], 0, s[10:11]
	s_mov_b32 m0, s28
	ds_read_b128 v[184:187], v151 offset:49152
	ds_read_b128 v[188:191], v151 offset:50176
	ds_read_b128 v[192:195], v151 offset:51200
	ds_read_b128 v[196:199], v151 offset:52224
	ds_read_b128 v[200:203], v151 offset:53248
	ds_read_b128 v[204:207], v151 offset:54272
	ds_read_b128 v[208:211], v151 offset:55296
	ds_read_b128 v[212:215], v151 offset:56320
	global_load_lds_dwordx4 v[146:147], off
	s_add_i32 m0, s28, 0x2000
	s_add_u32 s26, s26, 0x100080
	v_lshl_add_u64 v[146:147], v[216:217], 0, s[10:11]
	s_addc_u32 s27, s27, 0
	s_add_i32 s28, s59, s31
	global_load_lds_dwordx4 v[146:147], off
	v_lshl_add_u64 v[146:147], s[26:27], 0, v[130:131]
	s_mov_b32 m0, s28
	s_nop 0
	global_load_lds_dwordx4 v[146:147], off
	v_lshl_add_u64 v[146:147], s[26:27], 0, v[134:135]
	s_add_i32 m0, s28, 0x2000
	s_nop 0
	global_load_lds_dwordx4 v[146:147], off
	v_lshl_add_u64 v[146:147], v[218:219], 0, s[10:11]
	s_mov_b32 m0, s41
	s_nop 0
	global_load_lds_dwordx4 v[146:147], off
	v_lshl_add_u64 v[146:147], v[220:221], 0, s[10:11]
	s_mov_b32 m0, s42
	s_nop 0
	global_load_lds_dwordx4 v[146:147], off
	s_waitcnt vmcnt(8)
	s_waitcnt lgkmcnt(0)
	s_barrier
	s_setprio 1
	s_waitcnt lgkmcnt(0)
	v_mfma_f32_16x16x32_bf16 v[60:63], v[152:155], v[184:187], v[60:63]
	v_mfma_f32_16x16x32_bf16 v[56:59], v[160:163], v[184:187], v[56:59]
	v_mfma_f32_16x16x32_bf16 v[52:55], v[152:155], v[192:195], v[52:55]
	v_mfma_f32_16x16x32_bf16 v[44:47], v[160:163], v[192:195], v[44:47]
	v_mfma_f32_16x16x32_bf16 v[36:39], v[152:155], v[200:203], v[36:39]
	v_mfma_f32_16x16x32_bf16 v[28:31], v[160:163], v[200:203], v[28:31]
	v_mfma_f32_16x16x32_bf16 v[20:23], v[152:155], v[208:211], v[20:23]
	v_mfma_f32_16x16x32_bf16 v[12:15], v[160:163], v[208:211], v[12:15]
	v_mfma_f32_16x16x32_bf16 v[60:63], v[156:159], v[188:191], v[60:63]
	v_mfma_f32_16x16x32_bf16 v[56:59], v[164:167], v[188:191], v[56:59]
	v_mfma_f32_16x16x32_bf16 v[52:55], v[156:159], v[196:199], v[52:55]
	v_mfma_f32_16x16x32_bf16 v[44:47], v[164:167], v[196:199], v[44:47]
	v_mfma_f32_16x16x32_bf16 v[36:39], v[156:159], v[204:207], v[36:39]
	v_mfma_f32_16x16x32_bf16 v[28:31], v[164:167], v[204:207], v[28:31]
	v_mfma_f32_16x16x32_bf16 v[20:23], v[156:159], v[212:215], v[20:23]
	v_mfma_f32_16x16x32_bf16 v[12:15], v[164:167], v[212:215], v[12:15]
	s_setprio 0
	s_setprio 1
	v_mfma_f32_16x16x32_bf16 v[48:51], v[168:171], v[184:187], v[48:51]
	v_mfma_f32_16x16x32_bf16 v[40:43], v[176:179], v[184:187], v[40:43]
	v_mfma_f32_16x16x32_bf16 v[32:35], v[168:171], v[192:195], v[32:35]
	v_mfma_f32_16x16x32_bf16 v[24:27], v[176:179], v[192:195], v[24:27]
	v_mfma_f32_16x16x32_bf16 v[16:19], v[168:171], v[200:203], v[16:19]
	v_mfma_f32_16x16x32_bf16 v[8:11], v[176:179], v[200:203], v[8:11]
	v_mfma_f32_16x16x32_bf16 v[4:7], v[168:171], v[208:211], v[4:7]
	v_mfma_f32_16x16x32_bf16 v[0:3], v[176:179], v[208:211], v[0:3]
	v_mfma_f32_16x16x32_bf16 v[48:51], v[172:175], v[188:191], v[48:51]
	v_mfma_f32_16x16x32_bf16 v[40:43], v[180:183], v[188:191], v[40:43]
	v_mfma_f32_16x16x32_bf16 v[32:35], v[172:175], v[196:199], v[32:35]
	v_mfma_f32_16x16x32_bf16 v[24:27], v[180:183], v[196:199], v[24:27]
	v_mfma_f32_16x16x32_bf16 v[16:19], v[172:175], v[204:207], v[16:19]
	v_mfma_f32_16x16x32_bf16 v[8:11], v[180:183], v[204:207], v[8:11]
	v_mfma_f32_16x16x32_bf16 v[4:7], v[172:175], v[212:215], v[4:7]
	v_mfma_f32_16x16x32_bf16 v[0:3], v[180:183], v[212:215], v[0:3]
	s_setprio 0
	s_barrier
	s_add_i32 s57, s57, 2
	s_add_u32 s55, s55, 0x100
	s_addc_u32 s56, s56, 0
	s_add_u32 s24, s24, 0x100
	s_addc_u32 s25, s25, 0
	s_cmp_lt_u32 s57, 62
